# conv epilogue: v_pk_fma_f32 centre tap for channel pairs + v_mov_b64 commits and zero-inits, wider reschedule window
# speedup vs baseline: 1.0143x; 1.0027x over previous
; #define PG8_LAS __attribute__((address_space(3)))
;     __device__ __forceinline__ void run(f32x4 (&acc)[2][2][4][2], const Unit& un, int wr, int wc, int fr, int fq, PG8_LAS unsigned char* xl) const {
;     ...
;         for (int ai = 0; ai < 2; ++ai) { const int blk = ai * 2 + wr;
;             u32x2 keep[4];
; #pragma unroll
;             for (int n = 0; n < 2; ++n) {
;                 const int j = un.pn * 128 + cl + 4 * n;
;                 const f32x4 w0g = *(const PG8_GAS f32x4*)(cw + j), w1g = *(const PG8_GAS f32x4*)(cw + nup + j), w2g = *(const PG8_GAS f32x4*)(cw + 2 * (size_t)nup + j), bg = *(const PG8_GAS f32x4*)(cb + j);
;                 const f32x4 w0v = *(const PG8_GAS f32x4*)(cw + dff + j), w1v = *(const PG8_GAS f32x4*)(cw + nup + dff + j), w2v = *(const PG8_GAS f32x4*)(cw + 2 * (size_t)nup + dff + j), bv = *(const PG8_GAS f32x4*)(cb + dff + j);
;                 f32x4 hpg, hpv, hng, hnv;
;                 if (blk > 0) { hpg = *(const PG8_LAS f32x4*)(X + ((blk - 1) * 2 + 1) * 256 + cl + 4 * n); hpv = *(const PG8_LAS f32x4*)(X + ((blk - 1) * 2 + 1) * 256 + 128 + cl + 4 * n); } else { hpg = (f32x4){0.f, 0.f, 0.f, 0.f}; hpv = hpg; }
;                 if (blk < 3) { hng = *(const PG8_LAS f32x4*)(X + ((blk + 1) * 2 + 0) * 256 + cl + 4 * n); hnv = *(const PG8_LAS f32x4*)(X + ((blk + 1) * 2 + 0) * 256 + 128 + cl + 4 * n); } else { hng = (f32x4){0.f, 0.f, 0.f, 0.f}; hnv = hng; }
; #pragma unroll
;                 for (int m = 0; m < 4; ++m) {
;                     float o[4];
; #pragma unroll
;                     for (int e = 0; e < 4; ++e) {
;                         const float g = acc[ai][0][m][n][e], v = acc[ai][1][m][n][e];
;                         const float gpe = m > 0 ? PG8_ROR1(acc[ai][0][m - 1][n][e]) : hpg[e], vpe = m > 0 ? PG8_ROR1(acc[ai][1][m - 1][n][e]) : hpv[e];
;                         const float gne = m < 3 ? PG8_ROR15(acc[ai][0][m + 1][n][e]) : hng[e], vne = m < 3 ? PG8_ROR15(acc[ai][1][m + 1][n][e]) : hnv[e];
;                         const float gpi = PG8_ROR1(g), vpi = PG8_ROR1(v), gni = PG8_ROR15(g), vni = PG8_ROR15(v);
;                         const float gp = e0 ? gpe : gpi, vp = e0 ? vpe : vpi, gn = e15 ? gne : gni, vn = e15 ? vne : vni;
;                         const float cg = fma_s(w2g[e], gn, fma_s(w1g[e], g, fma_s(w0g[e], gp, bg[e]))), cv = fma_s(w2v[e], vn, fma_s(w1v[e], v, fma_s(w0v[e], vp, bv[e])));
.LBB0_794:
	s_or_b64 exec, exec, s[12:13]
	v_lshl_add_u32 v212, s10, 7, v196
	v_ashrrev_i32_e32 v213, 31, v212
	v_lshlrev_b64 v[158:159], 2, v[212:213]
	v_lshl_add_u64 v[192:193], s[20:21], 0, v[158:159]
	v_lshl_add_u64 v[198:199], s[48:49], 0, v[158:159]
	v_lshl_add_u64 v[194:195], s[22:23], 0, v[158:159]
	v_lshl_add_u64 v[202:203], s[52:53], 0, v[158:159]
	v_lshl_add_u64 v[206:207], s[56:57], 0, v[158:159]
	v_lshl_add_u64 v[208:209], s[58:59], 0, v[158:159]
	ds_read_b128 v[114:117], v247 offset:0
	v_lshl_add_u64 v[200:201], s[50:51], 0, v[158:159]
	ds_read_b128 v[138:141], v247 offset:512
	ds_read_b128 v[134:137], v247 offset:1024
	ds_read_b128 v[154:157], v247 offset:3072
	v_lshl_add_u64 v[204:205], s[54:55], 0, v[158:159]
	ds_read_b128 v[150:153], v247 offset:1536
	ds_read_b128 v[142:145], v247 offset:2048
	ds_read_b128 v[146:149], v247 offset:2560
	ds_read_b128 v[158:161], v247 offset:3584
	v_lshlrev_b32_e32 v197, 2, v196
	v_cndmask_b32_e64 v163, 0, 1, s[40:41]
	v_add_u32_e32 v215, s84, v197
	v_add_u32_e32 v217, s91, v197
	v_mov_b32_e32 v162, 0
	v_cmp_ne_u32_e64 s[14:15], 1, v163
	s_andn2_b64 vcc, exec, s[40:41]
	v_mov_b64_e32 v[170:171], 0
	v_mov_b64_e32 v[172:173], 0
	v_mov_b64_e32 v[174:175], 0
	v_mov_b64_e32 v[176:177], 0
	s_cbranch_vccnz .LBB0_796
	ds_read_b128 v[174:177], v217
	ds_read_b128 v[170:173], v215
.LBB0_796:
	v_cndmask_b32_e64 v163, 0, 1, s[42:43]
	v_lshl_add_u32 v246, v196, 2, s82
	v_cmp_ne_u32_e64 s[16:17], 1, v163
	s_andn2_b64 vcc, exec, s[42:43]
	v_mov_b32_e32 v163, 0
	v_mov_b64_e32 v[164:165], 0
	v_mov_b64_e32 v[166:167], 0
	v_mov_b64_e32 v[168:169], 0
	s_cbranch_vccnz .LBB0_798
	ds_read_b128 v[166:169], v246 offset:2048
	ds_read_b128 v[162:165], v246 offset:2560
.LBB0_798:
	v_fmamk_f32 v214, v214, 0x39800000, v244
	v_fmamk_f32 v216, v216, 0x39800000, v244
	v_rsq_f32_e32 v214, v214
	v_rsq_f32_e32 v216, v216
	v_cmp_eq_u32_e64 s[10:11], 0, v210
	v_cmp_eq_u32_e64 s[12:13], 15, v210
	v_pk_mul_f32 v[220:221], v[104:105], v[214:215] op_sel_hi:[1,0]
	v_pk_mul_f32 v[104:105], v[106:107], v[216:217] op_sel_hi:[1,0]
	s_waitcnt lgkmcnt(0)
	v_pk_mul_f32 v[110:111], v[110:111], v[214:215] op_sel_hi:[1,0]
	s_waitcnt lgkmcnt(0)
	v_pk_mul_f32 v[218:219], v[102:103], v[214:215] op_sel_hi:[1,0]
	v_pk_mul_f32 v[102:103], v[108:109], v[216:217] op_sel_hi:[1,0]
	v_pk_fma_f32 v[248:249], v[138:139], v[126:127], v[154:155]
	v_pk_fma_f32 v[224:225], v[142:143], v[130:131], v[158:159]
	v_pk_mul_f32 v[112:113], v[112:113], v[214:215] op_sel_hi:[1,0]
	v_fmac_f32_dpp v248, v126, v114 row_shr:1 row_mask:0xf bank_mask:0xf
	v_fmac_f32_dpp v249, v127, v115 row_shr:1 row_mask:0xf bank_mask:0xf
	v_fmac_f32_dpp v224, v130, v150 row_shr:1 row_mask:0xf bank_mask:0xf
	v_fmac_f32_dpp v248, v174, v114 row_shl:15 row_mask:0xf bank_mask:0xf
	v_fmac_f32_dpp v249, v175, v115 row_shl:15 row_mask:0xf bank_mask:0xf
	v_fmac_f32_dpp v225, v131, v151 row_shr:1 row_mask:0xf bank_mask:0xf
	v_fmac_f32_dpp v248, v126, v134 row_shl:1 row_mask:0xf bank_mask:0xf
	v_fmac_f32_dpp v249, v127, v135 row_shl:1 row_mask:0xf bank_mask:0xf
	v_fmac_f32_dpp v224, v170, v150 row_shl:15 row_mask:0xf bank_mask:0xf
	v_fmac_f32_dpp v248, v110, v134 row_shr:15 row_mask:0xf bank_mask:0xf
	v_fmac_f32_dpp v249, v111, v135 row_shr:15 row_mask:0xf bank_mask:0xf
	v_mov_b64_e32 v[174:175], v[248:249]
	v_fmac_f32_dpp v225, v171, v151 row_shl:15 row_mask:0xf bank_mask:0xf
	v_fmac_f32_dpp v224, v130, v146 row_shl:1 row_mask:0xf bank_mask:0xf
	v_pk_fma_f32 v[170:171], v[140:141], v[128:129], v[156:157]
	v_fmac_f32_dpp v225, v131, v147 row_shl:1 row_mask:0xf bank_mask:0xf
	v_fmac_f32_dpp v224, v218, v146 row_shr:15 row_mask:0xf bank_mask:0xf
	v_fmac_f32_dpp v170, v128, v116 row_shr:1 row_mask:0xf bank_mask:0xf
	v_fmac_f32_dpp v225, v219, v147 row_shr:15 row_mask:0xf bank_mask:0xf
	v_fmac_f32_dpp v171, v129, v117 row_shr:1 row_mask:0xf bank_mask:0xf
	v_fmac_f32_dpp v170, v176, v116 row_shl:15 row_mask:0xf bank_mask:0xf
	v_pk_mul_f32 v[98:99], v[98:99], v[216:217] op_sel_hi:[1,0]
	v_fmac_f32_dpp v171, v177, v117 row_shl:15 row_mask:0xf bank_mask:0xf
	v_fmac_f32_dpp v170, v128, v136 row_shl:1 row_mask:0xf bank_mask:0xf
	v_pk_fma_f32 v[176:177], v[144:145], v[132:133], v[160:161]
	v_fmac_f32_dpp v171, v129, v137 row_shl:1 row_mask:0xf bank_mask:0xf
	v_fmac_f32_dpp v170, v112, v136 row_shr:15 row_mask:0xf bank_mask:0xf
	v_fmac_f32_dpp v176, v132, v152 row_shr:1 row_mask:0xf bank_mask:0xf
	v_fmac_f32_dpp v171, v113, v137 row_shr:15 row_mask:0xf bank_mask:0xf
	v_fmac_f32_dpp v177, v133, v153 row_shr:1 row_mask:0xf bank_mask:0xf
	v_fmac_f32_dpp v176, v172, v152 row_shl:15 row_mask:0xf bank_mask:0xf
	v_pk_fma_f32 v[228:229], v[138:139], v[110:111], v[154:155]
	v_fmac_f32_dpp v177, v173, v153 row_shl:15 row_mask:0xf bank_mask:0xf
	v_fmac_f32_dpp v176, v132, v148 row_shl:1 row_mask:0xf bank_mask:0xf
	v_fmac_f32_dpp v228, v110, v114 row_shr:1 row_mask:0xf bank_mask:0xf
	v_fmac_f32_dpp v177, v133, v149 row_shl:1 row_mask:0xf bank_mask:0xf
	v_fmac_f32_dpp v176, v220, v148 row_shr:15 row_mask:0xf bank_mask:0xf
	v_fmac_f32_dpp v229, v111, v115 row_shr:1 row_mask:0xf bank_mask:0xf
	v_fmac_f32_dpp v177, v221, v149 row_shr:15 row_mask:0xf bank_mask:0xf
	v_fmac_f32_dpp v228, v126, v114 row_shl:15 row_mask:0xf bank_mask:0xf
	v_fmac_f32_dpp v229, v127, v115 row_shl:15 row_mask:0xf bank_mask:0xf
	v_pk_fma_f32 v[234:235], v[142:143], v[218:219], v[158:159]
	v_fmac_f32_dpp v228, v110, v134 row_shl:1 row_mask:0xf bank_mask:0xf
	v_fmac_f32_dpp v229, v111, v135 row_shl:1 row_mask:0xf bank_mask:0xf
	v_fmac_f32_dpp v234, v218, v150 row_shr:1 row_mask:0xf bank_mask:0xf
	v_fmac_f32_dpp v228, v104, v134 row_shr:15 row_mask:0xf bank_mask:0xf
; __device__ __forceinline__ float fma_s(float a, float b, float c) { float d; asm("v_fma_f32 %0, %1, %2, %3" : "=v"(d) : "v"(a), "v"(b), "v"(c)); return d; }
; #define PG8_ROR1(x) dpp_ror1(x)
; #define PG8_ROR15(x) dpp_ror15(x)
;     __device__ __forceinline__ void run(f32x4 (&acc)[2][2][4][2], const Unit& un, int wr, int wc, int fr, int fq, PG8_LAS unsigned char* xl) const {
;     ...
; #pragma unroll
;                 for (int m = 0; m < 4; ++m) {
;                     float o[4];
; #pragma unroll
;                     for (int e = 0; e < 4; ++e) {
;                         const float g = acc[ai][0][m][n][e], v = acc[ai][1][m][n][e];
;                         const float gpe = m > 0 ? PG8_ROR1(acc[ai][0][m - 1][n][e]) : hpg[e], vpe = m > 0 ? PG8_ROR1(acc[ai][1][m - 1][n][e]) : hpv[e];
;                         const float gne = m < 3 ? PG8_ROR15(acc[ai][0][m + 1][n][e]) : hng[e], vne = m < 3 ? PG8_ROR15(acc[ai][1][m + 1][n][e]) : hnv[e];
;                         const float gpi = PG8_ROR1(g), vpi = PG8_ROR1(v), gni = PG8_ROR15(g), vni = PG8_ROR15(v);
;                         const float gp = e0 ? gpe : gpi, vp = e0 ? vpe : vpi, gn = e15 ? gne : gni, vn = e15 ? vne : vni;
;                         const float cg = fma_s(w2g[e], gn, fma_s(w1g[e], g, fma_s(w0g[e], gp, bg[e]))), cv = fma_s(w2v[e], vn, fma_s(w1v[e], v, fma_s(w0v[e], vp, bv[e])));
;                         o[e] = (cg * cv) * __builtin_amdgcn_rcpf(1.0f + __builtin_amdgcn_exp2f(cg * -1.4426950408889634f));
;                     }
	v_fmac_f32_dpp v229, v105, v135 row_shr:15 row_mask:0xf bank_mask:0xf
	v_fmac_f32_dpp v235, v219, v151 row_shr:1 row_mask:0xf bank_mask:0xf
	v_fmac_f32_dpp v234, v130, v150 row_shl:15 row_mask:0xf bank_mask:0xf
	v_pk_mul_f32 v[100:101], v[100:101], v[216:217] op_sel_hi:[1,0]
	v_fmac_f32_dpp v235, v131, v151 row_shl:15 row_mask:0xf bank_mask:0xf
	v_fmac_f32_dpp v234, v218, v146 row_shl:1 row_mask:0xf bank_mask:0xf
	v_pk_fma_f32 v[250:251], v[140:141], v[112:113], v[156:157]
	v_pk_fma_f32 v[236:237], v[142:143], v[98:99], v[158:159]
	v_fmac_f32_dpp v235, v219, v147 row_shl:1 row_mask:0xf bank_mask:0xf
	v_fmac_f32_dpp v234, v98, v146 row_shr:15 row_mask:0xf bank_mask:0xf
	v_fmac_f32_dpp v250, v112, v116 row_shr:1 row_mask:0xf bank_mask:0xf
	v_fmac_f32_dpp v235, v99, v147 row_shr:15 row_mask:0xf bank_mask:0xf
	v_fmac_f32_dpp v251, v113, v117 row_shr:1 row_mask:0xf bank_mask:0xf
	v_fmac_f32_dpp v250, v128, v116 row_shl:15 row_mask:0xf bank_mask:0xf
	v_pk_fma_f32 v[226:227], v[144:145], v[220:221], v[160:161]
	v_fmac_f32_dpp v251, v129, v117 row_shl:15 row_mask:0xf bank_mask:0xf
	v_fmac_f32_dpp v250, v112, v136 row_shl:1 row_mask:0xf bank_mask:0xf
	v_fmac_f32_dpp v226, v220, v152 row_shr:1 row_mask:0xf bank_mask:0xf
	v_fmac_f32_dpp v251, v113, v137 row_shl:1 row_mask:0xf bank_mask:0xf
	v_fmac_f32_dpp v250, v102, v136 row_shr:15 row_mask:0xf bank_mask:0xf
	v_fmac_f32_dpp v227, v221, v153 row_shr:1 row_mask:0xf bank_mask:0xf
	v_fmac_f32_dpp v251, v103, v137 row_shr:15 row_mask:0xf bank_mask:0xf
	v_fmac_f32_dpp v226, v132, v152 row_shl:15 row_mask:0xf bank_mask:0xf
	v_fmac_f32_dpp v227, v133, v153 row_shl:15 row_mask:0xf bank_mask:0xf
	v_pk_fma_f32 v[232:233], v[138:139], v[104:105], v[154:155]
	v_fmac_f32_dpp v226, v220, v148 row_shl:1 row_mask:0xf bank_mask:0xf
	v_fmac_f32_dpp v227, v221, v149 row_shl:1 row_mask:0xf bank_mask:0xf
	v_fmac_f32_dpp v232, v104, v114 row_shr:1 row_mask:0xf bank_mask:0xf
	v_fmac_f32_dpp v226, v100, v148 row_shr:15 row_mask:0xf bank_mask:0xf
	v_fmac_f32_dpp v227, v101, v149 row_shr:15 row_mask:0xf bank_mask:0xf
	v_fmac_f32_dpp v233, v105, v115 row_shr:1 row_mask:0xf bank_mask:0xf
	v_fmac_f32_dpp v232, v110, v114 row_shl:15 row_mask:0xf bank_mask:0xf
	v_fmac_f32_dpp v236, v98, v150 row_shr:1 row_mask:0xf bank_mask:0xf
	v_fmac_f32_dpp v233, v111, v115 row_shl:15 row_mask:0xf bank_mask:0xf
	v_fmac_f32_dpp v232, v104, v134 row_shl:1 row_mask:0xf bank_mask:0xf
	v_fmac_f32_dpp v237, v99, v151 row_shr:1 row_mask:0xf bank_mask:0xf
	v_fmac_f32_dpp v233, v105, v135 row_shl:1 row_mask:0xf bank_mask:0xf
	v_fmac_f32_dpp v232, v118, v134 row_shr:15 row_mask:0xf bank_mask:0xf
	v_fmac_f32_dpp v236, v218, v150 row_shl:15 row_mask:0xf bank_mask:0xf
	v_fmac_f32_dpp v233, v119, v135 row_shr:15 row_mask:0xf bank_mask:0xf
	v_fmac_f32_dpp v237, v219, v151 row_shl:15 row_mask:0xf bank_mask:0xf
	v_mov_b64_e32 v[218:219], v[250:251]
	v_fmac_f32_dpp v236, v98, v146 row_shl:1 row_mask:0xf bank_mask:0xf
	v_fmac_f32_dpp v237, v99, v147 row_shl:1 row_mask:0xf bank_mask:0xf
	v_pk_fma_f32 v[172:173], v[140:141], v[102:103], v[156:157]
	v_fmac_f32_dpp v236, v122, v146 row_shr:15 row_mask:0xf bank_mask:0xf
	v_fmac_f32_dpp v237, v123, v147 row_shr:15 row_mask:0xf bank_mask:0xf
	v_fmac_f32_dpp v172, v102, v116 row_shr:1 row_mask:0xf bank_mask:0xf
	v_fmac_f32_dpp v173, v103, v117 row_shr:1 row_mask:0xf bank_mask:0xf
	v_pk_fma_f32 v[252:253], v[144:145], v[100:101], v[160:161]
	v_fmac_f32_dpp v172, v112, v116 row_shl:15 row_mask:0xf bank_mask:0xf
	v_fmac_f32_dpp v173, v113, v117 row_shl:15 row_mask:0xf bank_mask:0xf
	v_fmac_f32_dpp v252, v100, v152 row_shr:1 row_mask:0xf bank_mask:0xf
	v_fmac_f32_dpp v172, v102, v136 row_shl:1 row_mask:0xf bank_mask:0xf
	v_fmac_f32_dpp v173, v103, v137 row_shl:1 row_mask:0xf bank_mask:0xf
	v_fmac_f32_dpp v253, v101, v153 row_shr:1 row_mask:0xf bank_mask:0xf
	v_fmac_f32_dpp v172, v120, v136 row_shr:15 row_mask:0xf bank_mask:0xf
	v_fmac_f32_dpp v173, v121, v137 row_shr:15 row_mask:0xf bank_mask:0xf
	v_fmac_f32_dpp v252, v220, v152 row_shl:15 row_mask:0xf bank_mask:0xf
	v_fmac_f32_dpp v253, v221, v153 row_shl:15 row_mask:0xf bank_mask:0xf
	v_pk_fma_f32 v[222:223], v[138:139], v[118:119], v[154:155]
	v_fmac_f32_dpp v252, v100, v148 row_shl:1 row_mask:0xf bank_mask:0xf
	v_fmac_f32_dpp v253, v101, v149 row_shl:1 row_mask:0xf bank_mask:0xf
	v_fmac_f32_dpp v222, v118, v114 row_shr:1 row_mask:0xf bank_mask:0xf
	v_fmac_f32_dpp v252, v124, v148 row_shr:15 row_mask:0xf bank_mask:0xf
	v_fmac_f32_dpp v253, v125, v149 row_shr:15 row_mask:0xf bank_mask:0xf
	v_mov_b64_e32 v[220:221], v[252:253]
	v_fmac_f32_dpp v223, v119, v115 row_shr:1 row_mask:0xf bank_mask:0xf
	v_fmac_f32_dpp v222, v104, v114 row_shl:15 row_mask:0xf bank_mask:0xf
	v_pk_fma_f32 v[230:231], v[142:143], v[122:123], v[158:159]
	v_fmac_f32_dpp v223, v105, v115 row_shl:15 row_mask:0xf bank_mask:0xf
	v_fmac_f32_dpp v222, v118, v134 row_shl:1 row_mask:0xf bank_mask:0xf
	v_fmac_f32_dpp v230, v122, v150 row_shr:1 row_mask:0xf bank_mask:0xf
	v_fmac_f32_dpp v223, v119, v135 row_shl:1 row_mask:0xf bank_mask:0xf
	v_fmac_f32_dpp v222, v166, v134 row_shr:15 row_mask:0xf bank_mask:0xf
	v_fmac_f32_dpp v231, v123, v151 row_shr:1 row_mask:0xf bank_mask:0xf
	v_fmac_f32_dpp v223, v167, v135 row_shr:15 row_mask:0xf bank_mask:0xf
	v_fmac_f32_dpp v230, v98, v150 row_shl:15 row_mask:0xf bank_mask:0xf
	v_fmac_f32_dpp v231, v99, v151 row_shl:15 row_mask:0xf bank_mask:0xf
	v_pk_fma_f32 v[138:139], v[140:141], v[120:121], v[156:157]
	v_fmac_f32_dpp v230, v122, v146 row_shl:1 row_mask:0xf bank_mask:0xf
	v_fmac_f32_dpp v231, v123, v147 row_shl:1 row_mask:0xf bank_mask:0xf
; #define PG8_LAS __attribute__((address_space(3)))
;     __device__ __forceinline__ void run(f32x4 (&acc)[2][2][4][2], const Unit& un, int wr, int wc, int fr, int fq, PG8_LAS unsigned char* xl) const {
;     ...
;             for (int n = 0; n < 2; ++n) {
;                 const int j = un.pn * 128 + cl + 4 * n;
;                 const f32x4 w0g = *(const PG8_GAS f32x4*)(cw + j), w1g = *(const PG8_GAS f32x4*)(cw + nup + j), w2g = *(const PG8_GAS f32x4*)(cw + 2 * (size_t)nup + j), bg = *(const PG8_GAS f32x4*)(cb + j);
;                 const f32x4 w0v = *(const PG8_GAS f32x4*)(cw + dff + j), w1v = *(const PG8_GAS f32x4*)(cw + nup + dff + j), w2v = *(const PG8_GAS f32x4*)(cw + 2 * (size_t)nup + dff + j), bv = *(const PG8_GAS f32x4*)(cb + dff + j);
;                 f32x4 hpg, hpv, hng, hnv;
;                 if (blk > 0) { hpg = *(const PG8_LAS f32x4*)(X + ((blk - 1) * 2 + 1) * 256 + cl + 4 * n); hpv = *(const PG8_LAS f32x4*)(X + ((blk - 1) * 2 + 1) * 256 + 128 + cl + 4 * n); } else { hpg = (f32x4){0.f, 0.f, 0.f, 0.f}; hpv = hpg; }
;                 if (blk < 3) { hng = *(const PG8_LAS f32x4*)(X + ((blk + 1) * 2 + 0) * 256 + cl + 4 * n); hnv = *(const PG8_LAS f32x4*)(X + ((blk + 1) * 2 + 0) * 256 + 128 + cl + 4 * n); } else { hng = (f32x4){0.f, 0.f, 0.f, 0.f}; hnv = hng; }
; #pragma unroll
;                 for (int m = 0; m < 4; ++m) {
;                     float o[4];
; #pragma unroll
;                     for (int e = 0; e < 4; ++e) {
;                         const float g = acc[ai][0][m][n][e], v = acc[ai][1][m][n][e];
;                         const float gpe = m > 0 ? PG8_ROR1(acc[ai][0][m - 1][n][e]) : hpg[e], vpe = m > 0 ? PG8_ROR1(acc[ai][1][m - 1][n][e]) : hpv[e];
;                         const float gne = m < 3 ? PG8_ROR15(acc[ai][0][m + 1][n][e]) : hng[e], vne = m < 3 ? PG8_ROR15(acc[ai][1][m + 1][n][e]) : hnv[e];
;                         const float gpi = PG8_ROR1(g), vpi = PG8_ROR1(v), gni = PG8_ROR15(g), vni = PG8_ROR15(v);
;                         const float gp = e0 ? gpe : gpi, vp = e0 ? vpe : vpi, gn = e15 ? gne : gni, vn = e15 ? vne : vni;
;                         const float cg = fma_s(w2g[e], gn, fma_s(w1g[e], g, fma_s(w0g[e], gp, bg[e]))), cv = fma_s(w2v[e], vn, fma_s(w1v[e], v, fma_s(w0v[e], vp, bv[e])));
;                         o[e] = (cg * cv) * __builtin_amdgcn_rcpf(1.0f + __builtin_amdgcn_exp2f(cg * -1.4426950408889634f));
	v_fmac_f32_dpp v138, v120, v116 row_shr:1 row_mask:0xf bank_mask:0xf
	v_fmac_f32_dpp v230, v162, v146 row_shr:15 row_mask:0xf bank_mask:0xf
	v_fmac_f32_dpp v231, v163, v147 row_shr:15 row_mask:0xf bank_mask:0xf
	v_fmac_f32_dpp v139, v121, v117 row_shr:1 row_mask:0xf bank_mask:0xf
	v_fmac_f32_dpp v138, v102, v116 row_shl:15 row_mask:0xf bank_mask:0xf
	v_pk_fma_f32 v[154:155], v[144:145], v[124:125], v[160:161]
	v_fmac_f32_dpp v139, v103, v117 row_shl:15 row_mask:0xf bank_mask:0xf
	v_fmac_f32_dpp v138, v120, v136 row_shl:1 row_mask:0xf bank_mask:0xf
	v_fmac_f32_dpp v154, v124, v152 row_shr:1 row_mask:0xf bank_mask:0xf
	v_fmac_f32_dpp v139, v121, v137 row_shl:1 row_mask:0xf bank_mask:0xf
	v_fmac_f32_dpp v138, v168, v136 row_shr:15 row_mask:0xf bank_mask:0xf
	v_fmac_f32_dpp v155, v125, v153 row_shr:1 row_mask:0xf bank_mask:0xf
	v_fmac_f32_dpp v139, v169, v137 row_shr:15 row_mask:0xf bank_mask:0xf
	v_fmac_f32_dpp v154, v100, v152 row_shl:15 row_mask:0xf bank_mask:0xf
	v_fmac_f32_dpp v155, v101, v153 row_shl:15 row_mask:0xf bank_mask:0xf
	v_or_b32_e32 v102, 4, v212
	v_fmac_f32_dpp v154, v124, v148 row_shl:1 row_mask:0xf bank_mask:0xf
	v_fmac_f32_dpp v155, v125, v149 row_shl:1 row_mask:0xf bank_mask:0xf
	v_ashrrev_i32_e32 v103, 31, v102
	v_fmac_f32_dpp v154, v164, v148 row_shr:15 row_mask:0xf bank_mask:0xf
	v_fmac_f32_dpp v155, v165, v149 row_shr:15 row_mask:0xf bank_mask:0xf
	v_lshlrev_b64 v[126:127], 2, v[102:103]
	v_lshl_add_u64 v[156:157], s[48:49], 0, v[126:127]
	ds_read_b128 v[98:101], v247 offset:16
	v_lshl_add_u64 v[158:159], s[50:51], 0, v[126:127]
	ds_read_b128 v[106:109], v247 offset:528
	ds_read_b128 v[102:105], v247 offset:1040
	ds_read_b128 v[118:121], v247 offset:3088
	v_lshl_add_u64 v[160:161], s[52:53], 0, v[126:127]
	v_lshl_add_u64 v[164:165], s[56:57], 0, v[126:127]
	v_lshl_add_u64 v[166:167], s[58:59], 0, v[126:127]
	v_lshl_add_u64 v[162:163], s[54:55], 0, v[126:127]
	ds_read_b128 v[110:113], v247 offset:1552
	ds_read_b128 v[114:117], v247 offset:2064
	ds_read_b128 v[122:125], v247 offset:2576
	ds_read_b128 v[126:129], v247 offset:3600
	v_mov_b32_e32 v130, 0
	s_and_b64 vcc, exec, s[14:15]
	v_mov_b64_e32 v[144:145], 0
	v_mov_b64_e32 v[146:147], 0
	v_mov_b64_e32 v[148:149], 0
	v_mov_b64_e32 v[150:151], 0
	s_cbranch_vccnz .LBB0_800
	ds_read_b128 v[148:151], v217 offset:16
	ds_read_b128 v[144:147], v215 offset:16
.LBB0_800:
	s_and_b64 vcc, exec, s[16:17]
	v_mov_b32_e32 v131, 0
	v_mov_b64_e32 v[132:133], 0
	v_mov_b64_e32 v[134:135], 0
	v_mov_b64_e32 v[136:137], 0
	s_cbranch_vccnz .LBB0_802
	ds_read_b128 v[134:137], v246 offset:2064
	ds_read_b128 v[130:133], v246 offset:2576
.LBB0_802:
	v_mul_f32_e32 v140, 0xbfb8aa3b, v174
	v_mul_f32_e32 v141, 0xbfb8aa3b, v175
	v_exp_f32_e32 v140, v140
	v_exp_f32_e32 v141, v141
	v_pk_mul_f32 v[142:143], v[174:175], v[224:225]
	v_pk_mul_f32 v[152:153], v[170:171], v[176:177]
	v_add_f32_e32 v140, 1.0, v140
	v_add_f32_e32 v141, 1.0, v141
	v_rcp_f32_e32 v140, v140
	v_rcp_f32_e32 v141, v141
	v_pk_mul_f32 v[168:169], v[218:219], v[226:227]
	v_mov_b32_e32 v215, v214
	v_mov_b32_e32 v217, v216
	v_pk_mul_f32 v[140:141], v[142:143], v[140:141]
	v_mul_f32_e32 v142, 0xbfb8aa3b, v170
	v_mul_f32_e32 v143, 0xbfb8aa3b, v171
	v_exp_f32_e32 v142, v142
	v_exp_f32_e32 v143, v143
	v_pk_mul_f32 v[170:171], v[172:173], v[220:221]
	s_lshl_b32 s14, s76, 8
	v_add_f32_e32 v142, 1.0, v142
	v_add_f32_e32 v143, 1.0, v143
	v_rcp_f32_e32 v142, v142
	v_rcp_f32_e32 v143, v143
	s_add_i32 s14, s14, s34
	v_pk_mul_f32 v[142:143], v[152:153], v[142:143]
	v_cvt_pk_bf16_f32 v152, v140, v141
	v_mul_f32_e32 v140, 0xbfb8aa3b, v228
	v_mul_f32_e32 v141, 0xbfb8aa3b, v229
	v_exp_f32_e32 v140, v140
	v_exp_f32_e32 v141, v141
	v_cvt_pk_bf16_f32 v153, v142, v143
	v_pk_mul_f32 v[142:143], v[228:229], v[234:235]
	v_add_f32_e32 v140, 1.0, v140
	v_add_f32_e32 v141, 1.0, v141
	v_rcp_f32_e32 v140, v140
	v_rcp_f32_e32 v141, v141
	s_waitcnt lgkmcnt(1)
	v_pk_mul_f32 v[140:141], v[142:143], v[140:141]
	v_mul_f32_e32 v142, 0xbfb8aa3b, v218
	v_mul_f32_e32 v143, 0xbfb8aa3b, v219
	v_exp_f32_e32 v142, v142
	v_exp_f32_e32 v143, v143
	v_add_f32_e32 v142, 1.0, v142
	v_add_f32_e32 v143, 1.0, v143
	v_rcp_f32_e32 v142, v142
	v_rcp_f32_e32 v143, v143
	s_waitcnt lgkmcnt(0)
	v_pk_mul_f32 v[168:169], v[168:169], v[142:143]
	v_cvt_pk_bf16_f32 v142, v140, v141
	v_mul_f32_e32 v140, 0xbfb8aa3b, v232
	v_mul_f32_e32 v141, 0xbfb8aa3b, v233
	v_exp_f32_e32 v140, v140
	v_exp_f32_e32 v141, v141
	v_cvt_pk_bf16_f32 v143, v168, v169
	v_pk_mul_f32 v[168:169], v[232:233], v[236:237]
	v_add_f32_e32 v140, 1.0, v140
	v_add_f32_e32 v141, 1.0, v141
	v_rcp_f32_e32 v140, v140
	v_rcp_f32_e32 v141, v141
	s_waitcnt lgkmcnt(0)
	v_pk_mul_f32 v[140:141], v[168:169], v[140:141]
	v_mul_f32_e32 v168, 0xbfb8aa3b, v172
	v_mul_f32_e32 v169, 0xbfb8aa3b, v173
	v_exp_f32_e32 v168, v168
	v_exp_f32_e32 v169, v169
	v_cvt_pk_bf16_f32 v140, v140, v141
	v_add_u32_e32 v172, s14, v210
	v_add_f32_e32 v168, 1.0, v168
	v_add_f32_e32 v169, 1.0, v169
	v_rcp_f32_e32 v168, v168
	v_rcp_f32_e32 v169, v169
	s_waitcnt lgkmcnt(0)
; #define PG8_GAS __attribute__((address_space(1)))
; __device__ __forceinline__ unsigned cvt_pk_bf16(float lo, float hi) { const f32x2c v = {lo, hi}; return __builtin_bit_cast(unsigned, __builtin_convertvector(v, bf16x2c)); }
; __device__ __forceinline__ float fma_s(float a, float b, float c) { float d; asm("v_fma_f32 %0, %1, %2, %3" : "=v"(d) : "v"(a), "v"(b), "v"(c)); return d; }
; #define PG8_ROR1(x) dpp_ror1(x)
; #define PG8_ROR15(x) dpp_ror15(x)
;     __device__ __forceinline__ void run(f32x4 (&acc)[2][2][4][2], const Unit& un, int wr, int wc, int fr, int fq, PG8_LAS unsigned char* xl) const {
;     ...
;                 for (int m = 0; m < 4; ++m) {
;                     float o[4];
; #pragma unroll
;                     for (int e = 0; e < 4; ++e) {
;                         const float g = acc[ai][0][m][n][e], v = acc[ai][1][m][n][e];
;                         const float gpe = m > 0 ? PG8_ROR1(acc[ai][0][m - 1][n][e]) : hpg[e], vpe = m > 0 ? PG8_ROR1(acc[ai][1][m - 1][n][e]) : hpv[e];
;                         const float gne = m < 3 ? PG8_ROR15(acc[ai][0][m + 1][n][e]) : hng[e], vne = m < 3 ? PG8_ROR15(acc[ai][1][m + 1][n][e]) : hnv[e];
;                         const float gpi = PG8_ROR1(g), vpi = PG8_ROR1(v), gni = PG8_ROR15(g), vni = PG8_ROR15(v);
;                         const float gp = e0 ? gpe : gpi, vp = e0 ? vpe : vpi, gn = e15 ? gne : gni, vn = e15 ? vne : vni;
;                         const float cg = fma_s(w2g[e], gn, fma_s(w1g[e], g, fma_s(w0g[e], gp, bg[e]))), cv = fma_s(w2v[e], vn, fma_s(w1v[e], v, fma_s(w0v[e], vp, bv[e])));
;                         o[e] = (cg * cv) * __builtin_amdgcn_rcpf(1.0f + __builtin_amdgcn_exp2f(cg * -1.4426950408889634f));
;                     }
;                     if (n == 0) { keep[m].x = cvt_pk_bf16(o[0], o[1]); keep[m].y = cvt_pk_bf16(o[2], o[3]); }
;                     else { u32x4 w; w.x = keep[m].x; w.y = keep[m].y; w.z = cvt_pk_bf16(o[0], o[1]); w.w = cvt_pk_bf16(o[2], o[3]);
;                         *(PG8_GAS u32x4*)(act + (size_t)(row0 + ai * HALF + m * 16) * dff + j - 4) = w; }
	v_pk_mul_f32 v[168:169], v[170:171], v[168:169]
	v_cvt_pk_bf16_f32 v141, v168, v169
	v_mul_f32_e32 v168, 0xbfb8aa3b, v222
	v_mul_f32_e32 v169, 0xbfb8aa3b, v223
	v_exp_f32_e32 v168, v168
	v_exp_f32_e32 v169, v169
	v_pk_mul_f32 v[170:171], v[222:223], v[230:231]
	v_add_f32_e32 v168, 1.0, v168
	v_add_f32_e32 v169, 1.0, v169
	v_rcp_f32_e32 v168, v168
	v_rcp_f32_e32 v169, v169
	v_fma_f32 v179, v106, v90, v118
	v_pk_mul_f32 v[168:169], v[170:171], v[168:169]
	v_mul_f32_e32 v170, 0xbfb8aa3b, v138
	v_mul_f32_e32 v171, 0xbfb8aa3b, v139
	v_exp_f32_e32 v170, v170
	v_exp_f32_e32 v171, v171
	v_pk_mul_f32 v[138:139], v[138:139], v[154:155]
	v_add_f32_e32 v170, 1.0, v170
	v_add_f32_e32 v171, 1.0, v171
	v_rcp_f32_e32 v170, v170
	v_rcp_f32_e32 v171, v171
	v_fmac_f32_dpp v179, v90, v98 row_shr:1 row_mask:0xf bank_mask:0xf
	v_pk_mul_f32 v[154:155], v[138:139], v[170:171]
	v_cvt_pk_bf16_f32 v139, v154, v155
	v_mov_b32_e32 v154, v214
	v_mov_b32_e32 v155, v214
	v_cvt_pk_bf16_f32 v138, v168, v169
	v_pk_mul_f32 v[168:169], v[86:87], v[214:215]
	v_pk_mul_f32 v[86:87], v[80:81], v[154:155]
	v_pk_mul_f32 v[80:81], v[82:83], v[216:217]
	v_pk_mul_f32 v[82:83], v[74:75], v[216:217]
	v_pk_mul_f32 v[88:89], v[88:89], v[154:155]
	v_mov_b32_e32 v154, v216
	v_mov_b32_e32 v155, v216
	v_pk_mul_f32 v[170:171], v[78:79], v[214:215]
	v_pk_mul_f32 v[78:79], v[84:85], v[154:155]
	v_fmac_f32_dpp v179, v148, v98 row_shl:15 row_mask:0xf bank_mask:0xf
	v_pk_fma_f32 v[84:85], v[114:115], v[94:95], v[126:127]
	v_pk_mul_f32 v[76:77], v[76:77], v[154:155]
	v_fmac_f32_dpp v179, v90, v102 row_shl:1 row_mask:0xf bank_mask:0xf
	v_fmac_f32_dpp v84, v94, v110 row_shr:1 row_mask:0xf bank_mask:0xf
	v_fmac_f32_dpp v85, v95, v111 row_shr:1 row_mask:0xf bank_mask:0xf
	v_fmac_f32_dpp v179, v168, v102 row_shr:15 row_mask:0xf bank_mask:0xf
	v_mov_b32_e32 v74, v179
	v_fmac_f32_dpp v84, v144, v110 row_shl:15 row_mask:0xf bank_mask:0xf
	v_fmac_f32_dpp v85, v145, v111 row_shl:15 row_mask:0xf bank_mask:0xf
	v_mul_f32_e32 v75, 0xbfb8aa3b, v74
	v_fmac_f32_dpp v84, v94, v122 row_shl:1 row_mask:0xf bank_mask:0xf
	v_fmac_f32_dpp v85, v95, v123 row_shl:1 row_mask:0xf bank_mask:0xf
	v_exp_f32_e32 v75, v75
	v_fmac_f32_dpp v84, v170, v122 row_shr:15 row_mask:0xf bank_mask:0xf
	v_fmac_f32_dpp v85, v171, v123 row_shr:15 row_mask:0xf bank_mask:0xf
	v_add_f32_e32 v75, 1.0, v75
	v_rcp_f32_e32 v144, v75
	v_fma_f32 v75, v107, v91, v119
	v_fma_f32 v181, v108, v92, v120
	v_pk_fma_f32 v[248:249], v[116:117], v[96:97], v[128:129]
	v_fmac_f32_dpp v75, v91, v99 row_shr:1 row_mask:0xf bank_mask:0xf
	v_fmac_f32_dpp v181, v92, v100 row_shr:1 row_mask:0xf bank_mask:0xf
	v_fmac_f32_dpp v248, v96, v112 row_shr:1 row_mask:0xf bank_mask:0xf
	v_fmac_f32_dpp v75, v149, v99 row_shl:15 row_mask:0xf bank_mask:0xf
	v_fmac_f32_dpp v181, v150, v100 row_shl:15 row_mask:0xf bank_mask:0xf
	v_fmac_f32_dpp v249, v97, v113 row_shr:1 row_mask:0xf bank_mask:0xf
	v_fmac_f32_dpp v75, v91, v103 row_shl:1 row_mask:0xf bank_mask:0xf
	v_fmac_f32_dpp v181, v92, v104 row_shl:1 row_mask:0xf bank_mask:0xf
	v_fmac_f32_dpp v248, v146, v112 row_shl:15 row_mask:0xf bank_mask:0xf
	v_fmac_f32_dpp v75, v169, v103 row_shr:15 row_mask:0xf bank_mask:0xf
	v_mul_f32_e32 v145, 0xbfb8aa3b, v75
	v_exp_f32_e32 v145, v145
	v_pk_mul_f32 v[74:75], v[74:75], v[84:85]
	v_add_f32_e32 v145, 1.0, v145
	v_rcp_f32_e32 v145, v145
	v_fmac_f32_dpp v181, v88, v104 row_shr:15 row_mask:0xf bank_mask:0xf
	v_pk_mul_f32 v[74:75], v[74:75], v[144:145]
	v_mov_b32_e32 v84, v181
	v_fmac_f32_dpp v249, v147, v113 row_shl:15 row_mask:0xf bank_mask:0xf
	v_fmac_f32_dpp v248, v96, v124 row_shl:1 row_mask:0xf bank_mask:0xf
	v_mul_f32_e32 v85, 0xbfb8aa3b, v84
	v_fmac_f32_dpp v249, v97, v125 row_shl:1 row_mask:0xf bank_mask:0xf
	v_fmac_f32_dpp v248, v86, v124 row_shr:15 row_mask:0xf bank_mask:0xf
	v_exp_f32_e32 v85, v85
	v_fmac_f32_dpp v249, v87, v125 row_shr:15 row_mask:0xf bank_mask:0xf
	v_mov_b64_e32 v[144:145], v[248:249]
	v_add_f32_e32 v85, 1.0, v85
	v_rcp_f32_e32 v146, v85
	v_fma_f32 v85, v109, v93, v121
	v_cvt_pk_bf16_f32 v154, v74, v75
	v_mov_b64_e32 v[74:75], s[24:25]
	v_fmac_f32_dpp v85, v93, v101 row_shr:1 row_mask:0xf bank_mask:0xf
	v_fma_f32 v183, v106, v168, v118
	v_pk_fma_f32 v[250:251], v[114:115], v[170:171], v[126:127]
	v_fma_f32 v185, v107, v169, v119
	v_fmac_f32_dpp v85, v151, v101 row_shl:15 row_mask:0xf bank_mask:0xf
	v_fmac_f32_dpp v183, v168, v98 row_shr:1 row_mask:0xf bank_mask:0xf
	v_fmac_f32_dpp v250, v170, v110 row_shr:1 row_mask:0xf bank_mask:0xf
	v_fmac_f32_dpp v85, v93, v105 row_shl:1 row_mask:0xf bank_mask:0xf
	v_fmac_f32_dpp v183, v90, v98 row_shl:15 row_mask:0xf bank_mask:0xf
	v_fmac_f32_dpp v251, v171, v111 row_shr:1 row_mask:0xf bank_mask:0xf
	v_fmac_f32_dpp v85, v89, v105 row_shr:15 row_mask:0xf bank_mask:0xf
	v_mul_f32_e32 v147, 0xbfb8aa3b, v85
	v_exp_f32_e32 v147, v147
	v_pk_mul_f32 v[84:85], v[84:85], v[144:145]
	v_add_f32_e32 v147, 1.0, v147
	v_rcp_f32_e32 v147, v147
	v_fmac_f32_dpp v183, v168, v102 row_shl:1 row_mask:0xf bank_mask:0xf
	v_pk_mul_f32 v[84:85], v[84:85], v[146:147]
	v_cvt_pk_bf16_f32 v155, v84, v85
	v_mad_i64_i32 v[84:85], s[14:15], v172, s5, v[74:75]
	v_lshlrev_b64 v[146:147], 1, v[212:213]
	v_lshl_add_u64 v[84:85], v[84:85], 0, v[146:147]
	global_store_dwordx4 v[84:85], v[152:155], off
	v_fmac_f32_dpp v183, v80, v102 row_shr:15 row_mask:0xf bank_mask:0xf
	v_mov_b32_e32 v84, v183
	v_fmac_f32_dpp v250, v94, v110 row_shl:15 row_mask:0xf bank_mask:0xf
	v_fmac_f32_dpp v251, v95, v111 row_shl:15 row_mask:0xf bank_mask:0xf
	v_mul_f32_e32 v85, 0xbfb8aa3b, v84
	v_fmac_f32_dpp v250, v170, v122 row_shl:1 row_mask:0xf bank_mask:0xf
; #define PG8_GAS __attribute__((address_space(1)))
; __device__ __forceinline__ unsigned cvt_pk_bf16(float lo, float hi) { const f32x2c v = {lo, hi}; return __builtin_bit_cast(unsigned, __builtin_convertvector(v, bf16x2c)); }
; __device__ __forceinline__ float fma_s(float a, float b, float c) { float d; asm("v_fma_f32 %0, %1, %2, %3" : "=v"(d) : "v"(a), "v"(b), "v"(c)); return d; }
; #define PG8_ROR1(x) dpp_ror1(x)
; #define PG8_ROR15(x) dpp_ror15(x)
;     __device__ __forceinline__ void run(f32x4 (&acc)[2][2][4][2], const Unit& un, int wr, int wc, int fr, int fq, PG8_LAS unsigned char* xl) const {
;     ...
;                 for (int m = 0; m < 4; ++m) {
;                     float o[4];
; #pragma unroll
;                     for (int e = 0; e < 4; ++e) {
;                         const float g = acc[ai][0][m][n][e], v = acc[ai][1][m][n][e];
;                         const float gpe = m > 0 ? PG8_ROR1(acc[ai][0][m - 1][n][e]) : hpg[e], vpe = m > 0 ? PG8_ROR1(acc[ai][1][m - 1][n][e]) : hpv[e];
;                         const float gne = m < 3 ? PG8_ROR15(acc[ai][0][m + 1][n][e]) : hng[e], vne = m < 3 ? PG8_ROR15(acc[ai][1][m + 1][n][e]) : hnv[e];
;                         const float gpi = PG8_ROR1(g), vpi = PG8_ROR1(v), gni = PG8_ROR15(g), vni = PG8_ROR15(v);
;                         const float gp = e0 ? gpe : gpi, vp = e0 ? vpe : vpi, gn = e15 ? gne : gni, vn = e15 ? vne : vni;
;                         const float cg = fma_s(w2g[e], gn, fma_s(w1g[e], g, fma_s(w0g[e], gp, bg[e]))), cv = fma_s(w2v[e], vn, fma_s(w1v[e], v, fma_s(w0v[e], vp, bv[e])));
;                         o[e] = (cg * cv) * __builtin_amdgcn_rcpf(1.0f + __builtin_amdgcn_exp2f(cg * -1.4426950408889634f));
;                     }
;                     if (n == 0) { keep[m].x = cvt_pk_bf16(o[0], o[1]); keep[m].y = cvt_pk_bf16(o[2], o[3]); }
;                     else { u32x4 w; w.x = keep[m].x; w.y = keep[m].y; w.z = cvt_pk_bf16(o[0], o[1]); w.w = cvt_pk_bf16(o[2], o[3]);
;                         *(PG8_GAS u32x4*)(act + (size_t)(row0 + ai * HALF + m * 16) * dff + j - 4) = w; }
	v_fmac_f32_dpp v251, v171, v123 row_shl:1 row_mask:0xf bank_mask:0xf
	v_exp_f32_e32 v85, v85
	v_fmac_f32_dpp v250, v82, v122 row_shr:15 row_mask:0xf bank_mask:0xf
	v_fmac_f32_dpp v251, v83, v123 row_shr:15 row_mask:0xf bank_mask:0xf
	v_add_f32_e32 v85, 1.0, v85
	v_rcp_f32_e32 v94, v85
	v_fmac_f32_dpp v185, v169, v99 row_shr:1 row_mask:0xf bank_mask:0xf
	v_fma_f32 v255, v108, v88, v120
	v_fma_f32 v179, v108, v78, v120
	v_fma_f32 v181, v108, v68, v120
	v_fmac_f32_dpp v185, v91, v99 row_shl:15 row_mask:0xf bank_mask:0xf
	v_mov_b64_e32 v[90:91], v[250:251]
	v_fmac_f32_dpp v255, v88, v100 row_shr:1 row_mask:0xf bank_mask:0xf
	v_fmac_f32_dpp v185, v169, v103 row_shl:1 row_mask:0xf bank_mask:0xf
	v_pk_fma_f32 v[252:253], v[116:117], v[86:87], v[128:129]
	v_pk_fma_f32 v[248:249], v[116:117], v[76:77], v[128:129]
	v_fma_f32 v183, v116, v72, v128
	v_fma_f32 v250, v117, v73, v129
	v_fmac_f32_dpp v185, v81, v103 row_shr:15 row_mask:0xf bank_mask:0xf
	v_mov_b32_e32 v85, v185
	v_mul_f32_e32 v95, 0xbfb8aa3b, v85
	v_exp_f32_e32 v95, v95
	v_pk_mul_f32 v[84:85], v[84:85], v[90:91]
	v_add_f32_e32 v95, 1.0, v95
	v_rcp_f32_e32 v95, v95
	v_fmac_f32_dpp v255, v92, v100 row_shl:15 row_mask:0xf bank_mask:0xf
	v_pk_mul_f32 v[84:85], v[84:85], v[94:95]
	v_fmac_f32_dpp v252, v86, v112 row_shr:1 row_mask:0xf bank_mask:0xf
	v_fmac_f32_dpp v255, v88, v104 row_shl:1 row_mask:0xf bank_mask:0xf
	v_fmac_f32_dpp v253, v87, v113 row_shr:1 row_mask:0xf bank_mask:0xf
	v_fmac_f32_dpp v252, v96, v112 row_shl:15 row_mask:0xf bank_mask:0xf
	v_fmac_f32_dpp v255, v78, v104 row_shr:15 row_mask:0xf bank_mask:0xf
	v_fmac_f32_dpp v253, v97, v113 row_shl:15 row_mask:0xf bank_mask:0xf
	v_fmac_f32_dpp v252, v86, v124 row_shl:1 row_mask:0xf bank_mask:0xf
	v_cvt_pk_bf16_f32 v144, v84, v85
	v_fmac_f32_dpp v253, v87, v125 row_shl:1 row_mask:0xf bank_mask:0xf
	v_fmac_f32_dpp v252, v76, v124 row_shr:15 row_mask:0xf bank_mask:0xf
	v_add_u32_e32 v84, 16, v172
	v_fmac_f32_dpp v253, v77, v125 row_shr:15 row_mask:0xf bank_mask:0xf
	v_mad_i64_i32 v[84:85], s[14:15], v84, s5, v[74:75]
	v_lshl_add_u64 v[84:85], v[84:85], 0, v[146:147]
	v_fmac_f32_dpp v179, v78, v100 row_shr:1 row_mask:0xf bank_mask:0xf
	v_fmac_f32_dpp v248, v76, v112 row_shr:1 row_mask:0xf bank_mask:0xf
	v_fmac_f32_dpp v249, v77, v113 row_shr:1 row_mask:0xf bank_mask:0xf
	v_fmac_f32_dpp v179, v88, v100 row_shl:15 row_mask:0xf bank_mask:0xf
	v_mov_b32_e32 v88, v255
	v_mul_f32_e32 v90, 0xbfb8aa3b, v88
	v_exp_f32_e32 v90, v90
	v_fmac_f32_dpp v179, v78, v104 row_shl:1 row_mask:0xf bank_mask:0xf
	v_add_f32_e32 v90, 1.0, v90
	v_rcp_f32_e32 v90, v90
	v_fmac_f32_dpp v179, v68, v104 row_shr:15 row_mask:0xf bank_mask:0xf
	v_fmac_f32_dpp v248, v86, v112 row_shl:15 row_mask:0xf bank_mask:0xf
	v_fmac_f32_dpp v249, v87, v113 row_shl:15 row_mask:0xf bank_mask:0xf
	v_mov_b64_e32 v[86:87], v[252:253]
	v_fma_f32 v251, v109, v89, v121
	v_fma_f32 v185, v109, v79, v121
	v_fma_f32 v255, v109, v69, v121
	v_fmac_f32_dpp v251, v89, v101 row_shr:1 row_mask:0xf bank_mask:0xf
	v_fmac_f32_dpp v248, v76, v124 row_shl:1 row_mask:0xf bank_mask:0xf
	v_fmac_f32_dpp v249, v77, v125 row_shl:1 row_mask:0xf bank_mask:0xf
	v_fmac_f32_dpp v251, v93, v101 row_shl:15 row_mask:0xf bank_mask:0xf
	v_fmac_f32_dpp v248, v72, v124 row_shr:15 row_mask:0xf bank_mask:0xf
	v_fmac_f32_dpp v249, v73, v125 row_shr:15 row_mask:0xf bank_mask:0xf
	v_fmac_f32_dpp v251, v89, v105 row_shl:1 row_mask:0xf bank_mask:0xf
	v_fmac_f32_dpp v185, v79, v101 row_shr:1 row_mask:0xf bank_mask:0xf
	v_fmac_f32_dpp v181, v68, v100 row_shr:1 row_mask:0xf bank_mask:0xf
	v_fmac_f32_dpp v251, v79, v105 row_shr:15 row_mask:0xf bank_mask:0xf
	v_fmac_f32_dpp v185, v89, v101 row_shl:15 row_mask:0xf bank_mask:0xf
	v_mov_b32_e32 v89, v251
	v_mul_f32_e32 v91, 0xbfb8aa3b, v89
	v_exp_f32_e32 v91, v91
	v_pk_mul_f32 v[86:87], v[88:89], v[86:87]
	v_add_f32_e32 v91, 1.0, v91
	v_rcp_f32_e32 v91, v91
	v_fmac_f32_dpp v185, v79, v105 row_shl:1 row_mask:0xf bank_mask:0xf
	v_pk_mul_f32 v[86:87], v[86:87], v[90:91]
	v_cvt_pk_bf16_f32 v145, v86, v87
	global_store_dwordx4 v[84:85], v[142:145], off
	v_fmac_f32_dpp v185, v69, v105 row_shr:15 row_mask:0xf bank_mask:0xf
	v_fmac_f32_dpp v181, v78, v100 row_shl:15 row_mask:0xf bank_mask:0xf
	v_mov_b32_e32 v78, v179
	v_fmac_f32_dpp v183, v72, v112 row_shr:1 row_mask:0xf bank_mask:0xf
	v_fmac_f32_dpp v181, v68, v104 row_shl:1 row_mask:0xf bank_mask:0xf
	v_fmac_f32_dpp v255, v69, v101 row_shr:1 row_mask:0xf bank_mask:0xf
	v_fmac_f32_dpp v183, v76, v112 row_shl:15 row_mask:0xf bank_mask:0xf
	v_fmac_f32_dpp v181, v136, v104 row_shr:15 row_mask:0xf bank_mask:0xf
	v_mov_b32_e32 v68, v181
	v_fma_f32 v251, v106, v80, v118
	v_fma_f32 v179, v106, v66, v118
	v_fmac_f32_dpp v183, v72, v124 row_shl:1 row_mask:0xf bank_mask:0xf
	v_fmac_f32_dpp v251, v80, v98 row_shr:1 row_mask:0xf bank_mask:0xf
	v_fmac_f32_dpp v179, v66, v98 row_shr:1 row_mask:0xf bank_mask:0xf
	v_fmac_f32_dpp v183, v132, v124 row_shr:15 row_mask:0xf bank_mask:0xf
	v_fmac_f32_dpp v251, v168, v98 row_shl:15 row_mask:0xf bank_mask:0xf
	v_fmac_f32_dpp v179, v80, v98 row_shl:15 row_mask:0xf bank_mask:0xf
	v_fmac_f32_dpp v255, v79, v101 row_shl:15 row_mask:0xf bank_mask:0xf
	v_fmac_f32_dpp v251, v80, v102 row_shl:1 row_mask:0xf bank_mask:0xf
	v_mov_b32_e32 v79, v185
	v_fmac_f32_dpp v179, v66, v102 row_shl:1 row_mask:0xf bank_mask:0xf
	v_fmac_f32_dpp v251, v66, v102 row_shr:15 row_mask:0xf bank_mask:0xf
	v_mov_b32_e32 v80, v251
	v_pk_fma_f32 v[252:253], v[114:115], v[82:83], v[126:127]
	v_mul_f32_e32 v84, 0xbfb8aa3b, v80
	v_exp_f32_e32 v84, v84
	v_fmac_f32_dpp v252, v82, v110 row_shr:1 row_mask:0xf bank_mask:0xf
; #define PG8_ROR1(x) dpp_ror1(x)
;     __device__ __forceinline__ void run(f32x4 (&acc)[2][2][4][2], const Unit& un, int wr, int wc, int fr, int fq, PG8_LAS unsigned char* xl) const {
;     ...
;             for (int n = 0; n < 2; ++n) {
;                 const int j = un.pn * 128 + cl + 4 * n;
;                 const f32x4 w0g = *(const PG8_GAS f32x4*)(cw + j), w1g = *(const PG8_GAS f32x4*)(cw + nup + j), w2g = *(const PG8_GAS f32x4*)(cw + 2 * (size_t)nup + j), bg = *(const PG8_GAS f32x4*)(cb + j);
;                 const f32x4 w0v = *(const PG8_GAS f32x4*)(cw + dff + j), w1v = *(const PG8_GAS f32x4*)(cw + nup + dff + j), w2v = *(const PG8_GAS f32x4*)(cw + 2 * (size_t)nup + dff + j), bv = *(const PG8_GAS f32x4*)(cb + dff + j);
;                 f32x4 hpg, hpv, hng, hnv;
;                 if (blk > 0) { hpg = *(const PG8_LAS f32x4*)(X + ((blk - 1) * 2 + 1) * 256 + cl + 4 * n); hpv = *(const PG8_LAS f32x4*)(X + ((blk - 1) * 2 + 1) * 256 + 128 + cl + 4 * n); } else { hpg = (f32x4){0.f, 0.f, 0.f, 0.f}; hpv = hpg; }
;                 if (blk < 3) { hng = *(const PG8_LAS f32x4*)(X + ((blk + 1) * 2 + 0) * 256 + cl + 4 * n); hnv = *(const PG8_LAS f32x4*)(X + ((blk + 1) * 2 + 0) * 256 + 128 + cl + 4 * n); } else { hng = (f32x4){0.f, 0.f, 0.f, 0.f}; hnv = hng; }
; #pragma unroll
;                 for (int m = 0; m < 4; ++m) {
;                     float o[4];
; #pragma unroll
;                     for (int e = 0; e < 4; ++e) {
;                         const float g = acc[ai][0][m][n][e], v = acc[ai][1][m][n][e];
;                         const float gpe = m > 0 ? PG8_ROR1(acc[ai][0][m - 1][n][e]) : hpg[e], vpe = m > 0 ? PG8_ROR1(acc[ai][1][m - 1][n][e]) : hpv[e];
;                         const float gne = m < 3 ? PG8_ROR15(acc[ai][0][m + 1][n][e]) : hng[e], vne = m < 3 ? PG8_ROR15(acc[ai][1][m + 1][n][e]) : hnv[e];
;                         const float gpi = PG8_ROR1(g), vpi = PG8_ROR1(v), gni = PG8_ROR15(g), vni = PG8_ROR15(v);
;                         const float gp = e0 ? gpe : gpi, vp = e0 ? vpe : vpi, gn = e15 ? gne : gni, vn = e15 ? vne : vni;
;                         const float cg = fma_s(w2g[e], gn, fma_s(w1g[e], g, fma_s(w0g[e], gp, bg[e]))), cv = fma_s(w2v[e], vn, fma_s(w1v[e], v, fma_s(w0v[e], vp, bv[e])));
;                         o[e] = (cg * cv) * __builtin_amdgcn_rcpf(1.0f + __builtin_amdgcn_exp2f(cg * -1.4426950408889634f));
;                     }
	v_fmac_f32_dpp v253, v83, v111 row_shr:1 row_mask:0xf bank_mask:0xf
	v_add_f32_e32 v84, 1.0, v84
	v_fmac_f32_dpp v252, v170, v110 row_shl:15 row_mask:0xf bank_mask:0xf
	v_fmac_f32_dpp v253, v171, v111 row_shl:15 row_mask:0xf bank_mask:0xf
	v_rcp_f32_e32 v84, v84
	v_fmac_f32_dpp v252, v82, v122 row_shl:1 row_mask:0xf bank_mask:0xf
	v_fmac_f32_dpp v253, v83, v123 row_shl:1 row_mask:0xf bank_mask:0xf
	v_fmac_f32_dpp v179, v134, v102 row_shr:15 row_mask:0xf bank_mask:0xf
	v_fmac_f32_dpp v252, v70, v122 row_shr:15 row_mask:0xf bank_mask:0xf
	v_fmac_f32_dpp v253, v71, v123 row_shr:15 row_mask:0xf bank_mask:0xf
	v_mov_b32_e32 v66, v179
	v_fmac_f32_dpp v255, v69, v105 row_shl:1 row_mask:0xf bank_mask:0xf
	v_fmac_f32_dpp v250, v73, v113 row_shr:1 row_mask:0xf bank_mask:0xf
	v_add_u32_e32 v117, s93, v197
	v_fmac_f32_dpp v255, v137, v105 row_shr:15 row_mask:0xf bank_mask:0xf
	v_mov_b32_e32 v69, v255
	v_fma_f32 v181, v107, v81, v119
	v_fma_f32 v185, v107, v67, v119
	v_fmac_f32_dpp v250, v77, v113 row_shl:15 row_mask:0xf bank_mask:0xf
	v_fmac_f32_dpp v181, v81, v99 row_shr:1 row_mask:0xf bank_mask:0xf
	v_mov_b64_e32 v[76:77], v[248:249]
	v_pk_fma_f32 v[248:249], v[114:115], v[70:71], v[126:127]
	v_fmac_f32_dpp v181, v169, v99 row_shl:15 row_mask:0xf bank_mask:0xf
	v_pk_mul_f32 v[76:77], v[78:79], v[76:77]
	v_fmac_f32_dpp v248, v70, v110 row_shr:1 row_mask:0xf bank_mask:0xf
	v_fmac_f32_dpp v181, v81, v103 row_shl:1 row_mask:0xf bank_mask:0xf
	v_fmac_f32_dpp v249, v71, v111 row_shr:1 row_mask:0xf bank_mask:0xf
	v_fmac_f32_dpp v248, v82, v110 row_shl:15 row_mask:0xf bank_mask:0xf
	v_fmac_f32_dpp v181, v67, v103 row_shr:15 row_mask:0xf bank_mask:0xf
	v_fmac_f32_dpp v249, v83, v111 row_shl:15 row_mask:0xf bank_mask:0xf
	v_mov_b64_e32 v[82:83], v[252:253]
	v_fmac_f32_dpp v248, v70, v122 row_shl:1 row_mask:0xf bank_mask:0xf
	v_fmac_f32_dpp v249, v71, v123 row_shl:1 row_mask:0xf bank_mask:0xf
	v_fmac_f32_dpp v185, v67, v99 row_shr:1 row_mask:0xf bank_mask:0xf
	v_fmac_f32_dpp v248, v130, v122 row_shr:15 row_mask:0xf bank_mask:0xf
	v_fmac_f32_dpp v249, v131, v123 row_shr:15 row_mask:0xf bank_mask:0xf
	v_mov_b64_e32 v[70:71], v[248:249]
	v_fmac_f32_dpp v185, v81, v99 row_shl:15 row_mask:0xf bank_mask:0xf
	v_mov_b32_e32 v81, v181
	v_mul_f32_e32 v85, 0xbfb8aa3b, v81
	v_exp_f32_e32 v85, v85
	v_pk_mul_f32 v[80:81], v[80:81], v[82:83]
	v_add_f32_e32 v85, 1.0, v85
	v_rcp_f32_e32 v85, v85
	v_mul_f32_e32 v82, 0xbfb8aa3b, v78
	v_pk_mul_f32 v[80:81], v[80:81], v[84:85]
	v_exp_f32_e32 v82, v82
	v_mul_f32_e32 v83, 0xbfb8aa3b, v79
	v_exp_f32_e32 v83, v83
	v_add_f32_e32 v82, 1.0, v82
	v_rcp_f32_e32 v82, v82
	v_add_f32_e32 v83, 1.0, v83
	v_rcp_f32_e32 v83, v83
	v_cvt_pk_bf16_f32 v142, v80, v81
	v_pk_mul_f32 v[76:77], v[76:77], v[82:83]
	v_cvt_pk_bf16_f32 v143, v76, v77
	v_add_u32_e32 v76, 32, v172
	v_mad_i64_i32 v[76:77], s[14:15], v76, s5, v[74:75]
	v_lshl_add_u64 v[76:77], v[76:77], 0, v[146:147]
	global_store_dwordx4 v[76:77], v[140:143], off
	v_mul_f32_e32 v76, 0xbfb8aa3b, v66
	v_fmac_f32_dpp v185, v67, v103 row_shl:1 row_mask:0xf bank_mask:0xf
	v_exp_f32_e32 v76, v76
	v_fmac_f32_dpp v250, v73, v125 row_shl:1 row_mask:0xf bank_mask:0xf
	v_fmac_f32_dpp v185, v135, v103 row_shr:15 row_mask:0xf bank_mask:0xf
	v_mov_b32_e32 v67, v185
	v_mul_f32_e32 v77, 0xbfb8aa3b, v67
	v_exp_f32_e32 v77, v77
	v_add_f32_e32 v76, 1.0, v76
	v_rcp_f32_e32 v76, v76
	v_add_f32_e32 v77, 1.0, v77
	v_rcp_f32_e32 v77, v77
	v_pk_mul_f32 v[66:67], v[66:67], v[70:71]
	v_pk_mul_f32 v[66:67], v[66:67], v[76:77]
	v_mul_f32_e32 v71, 0xbfb8aa3b, v68
	v_exp_f32_e32 v71, v71
	v_mov_b32_e32 v70, v183
	v_add_f32_e32 v71, 1.0, v71
	v_rcp_f32_e32 v72, v71
	v_cvt_pk_bf16_f32 v140, v66, v67
	v_mul_f32_e32 v73, 0xbfb8aa3b, v69
	v_exp_f32_e32 v73, v73
	v_fmac_f32_dpp v250, v133, v125 row_shr:15 row_mask:0xf bank_mask:0xf
	v_mov_b32_e32 v71, v250
	v_add_u32_e32 v66, 48, v172
	v_pk_mul_f32 v[68:69], v[68:69], v[70:71]
	v_add_f32_e32 v73, 1.0, v73
	v_rcp_f32_e32 v73, v73
	v_mad_i64_i32 v[66:67], s[14:15], v66, s5, v[74:75]
	v_lshl_add_u64 v[66:67], v[66:67], 0, v[146:147]
	v_pk_mul_f32 v[68:69], v[68:69], v[72:73]
	v_cvt_pk_bf16_f32 v141, v68, v69
	global_store_dwordx4 v[66:67], v[138:141], off
	ds_read_b128 v[86:89], v247 offset:0
	ds_read_b128 v[82:85], v247 offset:512
	ds_read_b128 v[78:81], v247 offset:1024
	ds_read_b128 v[94:97], v247 offset:3072
	ds_read_b128 v[74:77], v247 offset:1536
	ds_read_b128 v[70:73], v247 offset:2048
	ds_read_b128 v[66:69], v247 offset:2560
	ds_read_b128 v[90:93], v247 offset:3584
	v_cndmask_b32_e64 v99, 0, 1, s[44:45]
	v_add_u32_e32 v115, s92, v197
	v_mov_b32_e32 v98, 0
	v_cmp_ne_u32_e64 s[14:15], 1, v99
	s_andn2_b64 vcc, exec, s[44:45]
	v_mov_b64_e32 v[106:107], 0
	v_mov_b64_e32 v[108:109], 0
	v_mov_b64_e32 v[110:111], 0
	v_mov_b64_e32 v[112:113], 0
	s_cbranch_vccnz .LBB0_804
	ds_read_b128 v[110:113], v117
	ds_read_b128 v[106:109], v115
.LBB0_804:
	v_cndmask_b32_e64 v99, 0, 1, s[46:47]
	v_lshl_add_u32 v134, v196, 2, s83
	v_cmp_ne_u32_e64 s[16:17], 1, v99
	s_andn2_b64 vcc, exec, s[46:47]
	v_mov_b32_e32 v99, 0
	v_mov_b64_e32 v[100:101], 0
	v_mov_b64_e32 v[102:103], 0
	v_mov_b64_e32 v[104:105], 0
	s_cbranch_vccnz .LBB0_806
	ds_read_b128 v[102:105], v134 offset:2048
	ds_read_b128 v[98:101], v134 offset:2560
;     __device__ __forceinline__ void run(f32x4 (&acc)[2][2][4][2], const Unit& un, int wr, int wc, int fr, int fq, PG8_LAS unsigned char* xl) const {
;     ...
;             for (int m = 0; m < 4; ++m) { const float iv = __builtin_amdgcn_rsqf(ssq[(size_t)un.pm * BM + wr * 64 + fr + ai * HALF + m * 16] * inv_n + eps);
; #pragma unroll
;                 for (int bj = 0; bj < 2; ++bj)
; #pragma unroll
;                     for (int n = 0; n < 2; ++n) acc[ai][bj][m][n] = acc[ai][bj][m][n] * iv; }
;     ...
;             for (int n = 0; n < 2; ++n) {
;                 const int j = un.pn * 128 + cl + 4 * n;
;                 const f32x4 w0g = *(const PG8_GAS f32x4*)(cw + j), w1g = *(const PG8_GAS f32x4*)(cw + nup + j), w2g = *(const PG8_GAS f32x4*)(cw + 2 * (size_t)nup + j), bg = *(const PG8_GAS f32x4*)(cb + j);
;                 const f32x4 w0v = *(const PG8_GAS f32x4*)(cw + dff + j), w1v = *(const PG8_GAS f32x4*)(cw + nup + dff + j), w2v = *(const PG8_GAS f32x4*)(cw + 2 * (size_t)nup + dff + j), bv = *(const PG8_GAS f32x4*)(cb + dff + j);
;                 f32x4 hpg, hpv, hng, hnv;
;                 if (blk > 0) { hpg = *(const PG8_LAS f32x4*)(X + ((blk - 1) * 2 + 1) * 256 + cl + 4 * n); hpv = *(const PG8_LAS f32x4*)(X + ((blk - 1) * 2 + 1) * 256 + 128 + cl + 4 * n); } else { hpg = (f32x4){0.f, 0.f, 0.f, 0.f}; hpv = hpg; }
;                 if (blk < 3) { hng = *(const PG8_LAS f32x4*)(X + ((blk + 1) * 2 + 0) * 256 + cl + 4 * n); hnv = *(const PG8_LAS f32x4*)(X + ((blk + 1) * 2 + 0) * 256 + 128 + cl + 4 * n); } else { hng = (f32x4){0.f, 0.f, 0.f, 0.f}; hnv = hng; }
; #pragma unroll
;                 for (int m = 0; m < 4; ++m) {
;                     float o[4];
; #pragma unroll
;                     for (int e = 0; e < 4; ++e) {
;                         const float g = acc[ai][0][m][n][e], v = acc[ai][1][m][n][e];
;                         const float gpe = m > 0 ? PG8_ROR1(acc[ai][0][m - 1][n][e]) : hpg[e], vpe = m > 0 ? PG8_ROR1(acc[ai][1][m - 1][n][e]) : hpv[e];
;                         const float gne = m < 3 ? PG8_ROR15(acc[ai][0][m + 1][n][e]) : hng[e], vne = m < 3 ? PG8_ROR15(acc[ai][1][m + 1][n][e]) : hnv[e];
;                         const float gpi = PG8_ROR1(g), vpi = PG8_ROR1(v), gni = PG8_ROR15(g), vni = PG8_ROR15(v);
;                         const float gp = e0 ? gpe : gpi, vp = e0 ? vpe : vpi, gn = e15 ? gne : gni, vn = e15 ? vne : vni;
.LBB0_806:
	v_fmamk_f32 v114, v245, 0x39800000, v244
	v_fmamk_f32 v116, v211, 0x39800000, v244
	v_rsq_f32_e32 v114, v114
	v_rsq_f32_e32 v116, v116
	v_pk_mul_f32 v[124:125], v[32:33], v[114:115] op_sel_hi:[1,0]
	v_pk_mul_f32 v[32:33], v[34:35], v[116:117] op_sel_hi:[1,0]
	s_waitcnt lgkmcnt(1)
	v_pk_mul_f32 v[42:43], v[42:43], v[114:115] op_sel_hi:[1,0]
	s_waitcnt lgkmcnt(0)
	v_pk_mul_f32 v[120:121], v[30:31], v[114:115] op_sel_hi:[1,0]
	v_pk_mul_f32 v[30:31], v[36:37], v[116:117] op_sel_hi:[1,0]
	s_waitcnt lgkmcnt(0)
	s_waitcnt lgkmcnt(0)
	v_pk_fma_f32 v[252:253], v[82:83], v[58:59], v[94:95]
	v_pk_mul_f32 v[44:45], v[44:45], v[114:115] op_sel_hi:[1,0]
	v_pk_fma_f32 v[248:249], v[84:85], v[60:61], v[96:97]
	v_fmac_f32_dpp v252, v58, v86 row_shr:1 row_mask:0xf bank_mask:0xf
	v_fmac_f32_dpp v253, v59, v87 row_shr:1 row_mask:0xf bank_mask:0xf
	v_fmac_f32_dpp v248, v60, v88 row_shr:1 row_mask:0xf bank_mask:0xf
	v_fmac_f32_dpp v252, v110, v86 row_shl:15 row_mask:0xf bank_mask:0xf
	v_fmac_f32_dpp v253, v111, v87 row_shl:15 row_mask:0xf bank_mask:0xf
	v_pk_fma_f32 v[110:111], v[70:71], v[62:63], v[90:91]
	v_fmac_f32_dpp v252, v58, v78 row_shl:1 row_mask:0xf bank_mask:0xf
	v_fmac_f32_dpp v253, v59, v79 row_shl:1 row_mask:0xf bank_mask:0xf
	v_fmac_f32_dpp v110, v62, v74 row_shr:1 row_mask:0xf bank_mask:0xf
	v_fmac_f32_dpp v252, v42, v78 row_shr:15 row_mask:0xf bank_mask:0xf
	v_fmac_f32_dpp v253, v43, v79 row_shr:15 row_mask:0xf bank_mask:0xf
	v_fmac_f32_dpp v111, v63, v75 row_shr:1 row_mask:0xf bank_mask:0xf
	v_fmac_f32_dpp v110, v106, v74 row_shl:15 row_mask:0xf bank_mask:0xf
	v_fmac_f32_dpp v249, v61, v89 row_shr:1 row_mask:0xf bank_mask:0xf
	v_fmac_f32_dpp v111, v107, v75 row_shl:15 row_mask:0xf bank_mask:0xf
	v_mov_b64_e32 v[106:107], v[252:253]
	v_fmac_f32_dpp v110, v62, v66 row_shl:1 row_mask:0xf bank_mask:0xf
	v_fmac_f32_dpp v111, v63, v67 row_shl:1 row_mask:0xf bank_mask:0xf
	v_fmac_f32_dpp v248, v112, v88 row_shl:15 row_mask:0xf bank_mask:0xf
	v_fmac_f32_dpp v110, v120, v66 row_shr:15 row_mask:0xf bank_mask:0xf
	v_fmac_f32_dpp v111, v121, v67 row_shr:15 row_mask:0xf bank_mask:0xf
	v_fmac_f32_dpp v249, v113, v89 row_shl:15 row_mask:0xf bank_mask:0xf
	v_pk_fma_f32 v[112:113], v[72:73], v[64:65], v[92:93]
	v_fmac_f32_dpp v248, v60, v80 row_shl:1 row_mask:0xf bank_mask:0xf
	v_fmac_f32_dpp v249, v61, v81 row_shl:1 row_mask:0xf bank_mask:0xf
	v_fmac_f32_dpp v112, v64, v76 row_shr:1 row_mask:0xf bank_mask:0xf
	v_fmac_f32_dpp v248, v44, v80 row_shr:15 row_mask:0xf bank_mask:0xf
	v_fmac_f32_dpp v249, v45, v81 row_shr:15 row_mask:0xf bank_mask:0xf
	v_fmac_f32_dpp v113, v65, v77 row_shr:1 row_mask:0xf bank_mask:0xf
	v_fmac_f32_dpp v112, v108, v76 row_shl:15 row_mask:0xf bank_mask:0xf
	v_pk_mul_f32 v[26:27], v[26:27], v[116:117] op_sel_hi:[1,0]
	v_fmac_f32_dpp v113, v109, v77 row_shl:15 row_mask:0xf bank_mask:0xf
	v_mov_b64_e32 v[108:109], v[248:249]
	v_fmac_f32_dpp v112, v64, v68 row_shl:1 row_mask:0xf bank_mask:0xf
	v_fmac_f32_dpp v113, v65, v69 row_shl:1 row_mask:0xf bank_mask:0xf
	v_pk_fma_f32 v[118:119], v[82:83], v[42:43], v[94:95]
	v_fmac_f32_dpp v112, v124, v68 row_shr:15 row_mask:0xf bank_mask:0xf
	v_fmac_f32_dpp v113, v125, v69 row_shr:15 row_mask:0xf bank_mask:0xf
	v_fmac_f32_dpp v118, v42, v86 row_shr:1 row_mask:0xf bank_mask:0xf
	v_fmac_f32_dpp v119, v43, v87 row_shr:1 row_mask:0xf bank_mask:0xf
	v_pk_fma_f32 v[250:251], v[70:71], v[120:121], v[90:91]
	v_pk_fma_f32 v[128:129], v[70:71], v[26:27], v[90:91]
	v_fmac_f32_dpp v118, v58, v86 row_shl:15 row_mask:0xf bank_mask:0xf
	v_fmac_f32_dpp v119, v59, v87 row_shl:15 row_mask:0xf bank_mask:0xf
	v_fmac_f32_dpp v250, v120, v74 row_shr:1 row_mask:0xf bank_mask:0xf
	v_fmac_f32_dpp v118, v42, v78 row_shl:1 row_mask:0xf bank_mask:0xf
	v_fmac_f32_dpp v119, v43, v79 row_shl:1 row_mask:0xf bank_mask:0xf
	v_fmac_f32_dpp v251, v121, v75 row_shr:1 row_mask:0xf bank_mask:0xf
	v_fmac_f32_dpp v118, v32, v78 row_shr:15 row_mask:0xf bank_mask:0xf
	v_fmac_f32_dpp v119, v33, v79 row_shr:15 row_mask:0xf bank_mask:0xf
	v_fmac_f32_dpp v250, v62, v74 row_shl:15 row_mask:0xf bank_mask:0xf
	v_fmac_f32_dpp v251, v63, v75 row_shl:15 row_mask:0xf bank_mask:0xf
	v_pk_mul_f32 v[28:29], v[28:29], v[116:117] op_sel_hi:[1,0]
	v_fmac_f32_dpp v250, v120, v66 row_shl:1 row_mask:0xf bank_mask:0xf
	v_fmac_f32_dpp v251, v121, v67 row_shl:1 row_mask:0xf bank_mask:0xf
	v_pk_fma_f32 v[122:123], v[84:85], v[44:45], v[96:97]
	v_fmac_f32_dpp v250, v26, v66 row_shr:15 row_mask:0xf bank_mask:0xf
	v_fmac_f32_dpp v251, v27, v67 row_shr:15 row_mask:0xf bank_mask:0xf
	v_fmac_f32_dpp v122, v44, v88 row_shr:1 row_mask:0xf bank_mask:0xf
	v_fmac_f32_dpp v123, v45, v89 row_shr:1 row_mask:0xf bank_mask:0xf
	v_pk_fma_f32 v[252:253], v[72:73], v[124:125], v[92:93]
	v_pk_fma_f32 v[132:133], v[72:73], v[28:29], v[92:93]
	v_fmac_f32_dpp v122, v60, v88 row_shl:15 row_mask:0xf bank_mask:0xf
	v_fmac_f32_dpp v123, v61, v89 row_shl:15 row_mask:0xf bank_mask:0xf
	v_fmac_f32_dpp v252, v124, v76 row_shr:1 row_mask:0xf bank_mask:0xf
	v_fmac_f32_dpp v122, v44, v80 row_shl:1 row_mask:0xf bank_mask:0xf
	v_fmac_f32_dpp v123, v45, v81 row_shl:1 row_mask:0xf bank_mask:0xf
	v_fmac_f32_dpp v253, v125, v77 row_shr:1 row_mask:0xf bank_mask:0xf
	v_fmac_f32_dpp v122, v30, v80 row_shr:15 row_mask:0xf bank_mask:0xf
	v_fmac_f32_dpp v123, v31, v81 row_shr:15 row_mask:0xf bank_mask:0xf
	v_fmac_f32_dpp v252, v64, v76 row_shl:15 row_mask:0xf bank_mask:0xf
	v_fmac_f32_dpp v253, v65, v77 row_shl:15 row_mask:0xf bank_mask:0xf
	v_pk_fma_f32 v[126:127], v[82:83], v[32:33], v[94:95]
	v_fmac_f32_dpp v252, v124, v68 row_shl:1 row_mask:0xf bank_mask:0xf
; #define PG8_ROR1(x) dpp_ror1(x)
;     __device__ __forceinline__ void run(f32x4 (&acc)[2][2][4][2], const Unit& un, int wr, int wc, int fr, int fq, PG8_LAS unsigned char* xl) const {
;     ...
;             for (int n = 0; n < 2; ++n) {
;                 const int j = un.pn * 128 + cl + 4 * n;
;                 const f32x4 w0g = *(const PG8_GAS f32x4*)(cw + j), w1g = *(const PG8_GAS f32x4*)(cw + nup + j), w2g = *(const PG8_GAS f32x4*)(cw + 2 * (size_t)nup + j), bg = *(const PG8_GAS f32x4*)(cb + j);
;                 const f32x4 w0v = *(const PG8_GAS f32x4*)(cw + dff + j), w1v = *(const PG8_GAS f32x4*)(cw + nup + dff + j), w2v = *(const PG8_GAS f32x4*)(cw + 2 * (size_t)nup + dff + j), bv = *(const PG8_GAS f32x4*)(cb + dff + j);
;                 f32x4 hpg, hpv, hng, hnv;
;                 if (blk > 0) { hpg = *(const PG8_LAS f32x4*)(X + ((blk - 1) * 2 + 1) * 256 + cl + 4 * n); hpv = *(const PG8_LAS f32x4*)(X + ((blk - 1) * 2 + 1) * 256 + 128 + cl + 4 * n); } else { hpg = (f32x4){0.f, 0.f, 0.f, 0.f}; hpv = hpg; }
;                 if (blk < 3) { hng = *(const PG8_LAS f32x4*)(X + ((blk + 1) * 2 + 0) * 256 + cl + 4 * n); hnv = *(const PG8_LAS f32x4*)(X + ((blk + 1) * 2 + 0) * 256 + 128 + cl + 4 * n); } else { hng = (f32x4){0.f, 0.f, 0.f, 0.f}; hnv = hng; }
; #pragma unroll
;                 for (int m = 0; m < 4; ++m) {
;                     float o[4];
; #pragma unroll
;                     for (int e = 0; e < 4; ++e) {
;                         const float g = acc[ai][0][m][n][e], v = acc[ai][1][m][n][e];
;                         const float gpe = m > 0 ? PG8_ROR1(acc[ai][0][m - 1][n][e]) : hpg[e], vpe = m > 0 ? PG8_ROR1(acc[ai][1][m - 1][n][e]) : hpv[e];
;                         const float gne = m < 3 ? PG8_ROR15(acc[ai][0][m + 1][n][e]) : hng[e], vne = m < 3 ? PG8_ROR15(acc[ai][1][m + 1][n][e]) : hnv[e];
;                         const float gpi = PG8_ROR1(g), vpi = PG8_ROR1(v), gni = PG8_ROR15(g), vni = PG8_ROR15(v);
;                         const float gp = e0 ? gpe : gpi, vp = e0 ? vpe : vpi, gn = e15 ? gne : gni, vn = e15 ? vne : vni;
;                         const float cg = fma_s(w2g[e], gn, fma_s(w1g[e], g, fma_s(w0g[e], gp, bg[e]))), cv = fma_s(w2v[e], vn, fma_s(w1v[e], v, fma_s(w0v[e], vp, bv[e])));
;                         o[e] = (cg * cv) * __builtin_amdgcn_rcpf(1.0f + __builtin_amdgcn_exp2f(cg * -1.4426950408889634f));
;                     }
	v_fmac_f32_dpp v253, v125, v69 row_shl:1 row_mask:0xf bank_mask:0xf
	v_fmac_f32_dpp v126, v32, v86 row_shr:1 row_mask:0xf bank_mask:0xf
	v_fmac_f32_dpp v252, v28, v68 row_shr:15 row_mask:0xf bank_mask:0xf
	v_fmac_f32_dpp v253, v29, v69 row_shr:15 row_mask:0xf bank_mask:0xf
	v_fmac_f32_dpp v127, v33, v87 row_shr:1 row_mask:0xf bank_mask:0xf
	v_fmac_f32_dpp v126, v42, v86 row_shl:15 row_mask:0xf bank_mask:0xf
	v_fmac_f32_dpp v128, v26, v74 row_shr:1 row_mask:0xf bank_mask:0xf
	v_fmac_f32_dpp v127, v43, v87 row_shl:15 row_mask:0xf bank_mask:0xf
	v_fmac_f32_dpp v126, v32, v78 row_shl:1 row_mask:0xf bank_mask:0xf
	v_fmac_f32_dpp v129, v27, v75 row_shr:1 row_mask:0xf bank_mask:0xf
	v_fmac_f32_dpp v127, v33, v79 row_shl:1 row_mask:0xf bank_mask:0xf
	v_fmac_f32_dpp v126, v50, v78 row_shr:15 row_mask:0xf bank_mask:0xf
	v_fmac_f32_dpp v128, v120, v74 row_shl:15 row_mask:0xf bank_mask:0xf
	v_fmac_f32_dpp v127, v51, v79 row_shr:15 row_mask:0xf bank_mask:0xf
	v_fmac_f32_dpp v129, v121, v75 row_shl:15 row_mask:0xf bank_mask:0xf
	v_mov_b64_e32 v[120:121], v[250:251]
	v_fmac_f32_dpp v128, v26, v66 row_shl:1 row_mask:0xf bank_mask:0xf
	v_fmac_f32_dpp v129, v27, v67 row_shl:1 row_mask:0xf bank_mask:0xf
	v_pk_fma_f32 v[130:131], v[84:85], v[30:31], v[96:97]
	v_fmac_f32_dpp v128, v54, v66 row_shr:15 row_mask:0xf bank_mask:0xf
	v_fmac_f32_dpp v129, v55, v67 row_shr:15 row_mask:0xf bank_mask:0xf
	v_fmac_f32_dpp v130, v30, v88 row_shr:1 row_mask:0xf bank_mask:0xf
	v_fmac_f32_dpp v131, v31, v89 row_shr:1 row_mask:0xf bank_mask:0xf
	v_fmac_f32_dpp v132, v28, v76 row_shr:1 row_mask:0xf bank_mask:0xf
	v_fmac_f32_dpp v130, v44, v88 row_shl:15 row_mask:0xf bank_mask:0xf
	v_fmac_f32_dpp v131, v45, v89 row_shl:15 row_mask:0xf bank_mask:0xf
	v_fmac_f32_dpp v133, v29, v77 row_shr:1 row_mask:0xf bank_mask:0xf
	v_fmac_f32_dpp v130, v30, v80 row_shl:1 row_mask:0xf bank_mask:0xf
	v_fmac_f32_dpp v131, v31, v81 row_shl:1 row_mask:0xf bank_mask:0xf
	v_fmac_f32_dpp v132, v124, v76 row_shl:15 row_mask:0xf bank_mask:0xf
	v_fmac_f32_dpp v130, v52, v80 row_shr:15 row_mask:0xf bank_mask:0xf
	v_fmac_f32_dpp v131, v53, v81 row_shr:15 row_mask:0xf bank_mask:0xf
	v_fmac_f32_dpp v133, v125, v77 row_shl:15 row_mask:0xf bank_mask:0xf
	v_mov_b64_e32 v[124:125], v[252:253]
	v_fmac_f32_dpp v132, v28, v68 row_shl:1 row_mask:0xf bank_mask:0xf
	v_fmac_f32_dpp v133, v29, v69 row_shl:1 row_mask:0xf bank_mask:0xf
	v_pk_fma_f32 v[94:95], v[82:83], v[50:51], v[94:95]
	v_fmac_f32_dpp v132, v56, v68 row_shr:15 row_mask:0xf bank_mask:0xf
	v_fmac_f32_dpp v133, v57, v69 row_shr:15 row_mask:0xf bank_mask:0xf
	v_fmac_f32_dpp v94, v50, v86 row_shr:1 row_mask:0xf bank_mask:0xf
	v_fmac_f32_dpp v95, v51, v87 row_shr:1 row_mask:0xf bank_mask:0xf
	v_pk_fma_f32 v[90:91], v[70:71], v[54:55], v[90:91]
	v_fmac_f32_dpp v94, v32, v86 row_shl:15 row_mask:0xf bank_mask:0xf
	v_fmac_f32_dpp v95, v33, v87 row_shl:15 row_mask:0xf bank_mask:0xf
	v_fmac_f32_dpp v90, v54, v74 row_shr:1 row_mask:0xf bank_mask:0xf
	v_fmac_f32_dpp v94, v50, v78 row_shl:1 row_mask:0xf bank_mask:0xf
	v_fmac_f32_dpp v95, v51, v79 row_shl:1 row_mask:0xf bank_mask:0xf
	v_fmac_f32_dpp v91, v55, v75 row_shr:1 row_mask:0xf bank_mask:0xf
	v_fmac_f32_dpp v94, v102, v78 row_shr:15 row_mask:0xf bank_mask:0xf
	v_fmac_f32_dpp v95, v103, v79 row_shr:15 row_mask:0xf bank_mask:0xf
	v_fmac_f32_dpp v90, v26, v74 row_shl:15 row_mask:0xf bank_mask:0xf
	v_fmac_f32_dpp v91, v27, v75 row_shl:15 row_mask:0xf bank_mask:0xf
	v_pk_fma_f32 v[248:249], v[84:85], v[52:53], v[96:97]
	v_fmac_f32_dpp v90, v54, v66 row_shl:1 row_mask:0xf bank_mask:0xf
	v_fmac_f32_dpp v91, v55, v67 row_shl:1 row_mask:0xf bank_mask:0xf
	v_fmac_f32_dpp v248, v52, v88 row_shr:1 row_mask:0xf bank_mask:0xf
	v_fmac_f32_dpp v90, v98, v66 row_shr:15 row_mask:0xf bank_mask:0xf
	v_fmac_f32_dpp v91, v99, v67 row_shr:15 row_mask:0xf bank_mask:0xf
	v_fmac_f32_dpp v249, v53, v89 row_shr:1 row_mask:0xf bank_mask:0xf
	v_fmac_f32_dpp v248, v30, v88 row_shl:15 row_mask:0xf bank_mask:0xf
	v_pk_fma_f32 v[92:93], v[72:73], v[56:57], v[92:93]
	v_fmac_f32_dpp v249, v31, v89 row_shl:15 row_mask:0xf bank_mask:0xf
	v_fmac_f32_dpp v248, v52, v80 row_shl:1 row_mask:0xf bank_mask:0xf
	v_fmac_f32_dpp v92, v56, v76 row_shr:1 row_mask:0xf bank_mask:0xf
	v_fmac_f32_dpp v249, v53, v81 row_shl:1 row_mask:0xf bank_mask:0xf
	v_fmac_f32_dpp v248, v104, v80 row_shr:15 row_mask:0xf bank_mask:0xf
	v_fmac_f32_dpp v93, v57, v77 row_shr:1 row_mask:0xf bank_mask:0xf
	v_fmac_f32_dpp v249, v105, v81 row_shr:15 row_mask:0xf bank_mask:0xf
	v_mov_b64_e32 v[88:89], v[248:249]
	v_fmac_f32_dpp v92, v28, v76 row_shl:15 row_mask:0xf bank_mask:0xf
	v_fmac_f32_dpp v93, v29, v77 row_shl:15 row_mask:0xf bank_mask:0xf
	ds_read_b128 v[62:65], v247 offset:16
	v_fmac_f32_dpp v92, v56, v68 row_shl:1 row_mask:0xf bank_mask:0xf
	v_fmac_f32_dpp v93, v57, v69 row_shl:1 row_mask:0xf bank_mask:0xf
	ds_read_b128 v[58:61], v247 offset:528
	v_fmac_f32_dpp v92, v100, v68 row_shr:15 row_mask:0xf bank_mask:0xf
	v_fmac_f32_dpp v93, v101, v69 row_shr:15 row_mask:0xf bank_mask:0xf
	ds_read_b128 v[54:57], v247 offset:1040
	ds_read_b128 v[66:69], v247 offset:3088
	ds_read_b128 v[34:37], v247 offset:1552
	ds_read_b128 v[26:29], v247 offset:2064
	ds_read_b128 v[30:33], v247 offset:2576
	ds_read_b128 v[42:45], v247 offset:3600
	v_mov_b32_e32 v50, 0
	s_and_b64 vcc, exec, s[14:15]
	v_mov_b64_e32 v[74:75], 0
	v_mov_b64_e32 v[76:77], 0
	v_mov_b64_e32 v[78:79], 0
	v_mov_b64_e32 v[80:81], 0
	s_cbranch_vccnz .LBB0_808
	ds_read_b128 v[78:81], v117 offset:16
	ds_read_b128 v[74:77], v115 offset:16
; #define PG8_GAS __attribute__((address_space(1)))
; __device__ __forceinline__ unsigned cvt_pk_bf16(float lo, float hi) { const f32x2c v = {lo, hi}; return __builtin_bit_cast(unsigned, __builtin_convertvector(v, bf16x2c)); }
; __device__ __forceinline__ float fma_s(float a, float b, float c) { float d; asm("v_fma_f32 %0, %1, %2, %3" : "=v"(d) : "v"(a), "v"(b), "v"(c)); return d; }
; #define PG8_ROR1(x) dpp_ror1(x)
;     __device__ __forceinline__ void run(f32x4 (&acc)[2][2][4][2], const Unit& un, int wr, int wc, int fr, int fq, PG8_LAS unsigned char* xl) const {
;     ...
;             for (int m = 0; m < 4; ++m) { const float iv = __builtin_amdgcn_rsqf(ssq[(size_t)un.pm * BM + wr * 64 + fr + ai * HALF + m * 16] * inv_n + eps);
; #pragma unroll
;                 for (int bj = 0; bj < 2; ++bj)
; #pragma unroll
;                     for (int n = 0; n < 2; ++n) acc[ai][bj][m][n] = acc[ai][bj][m][n] * iv; }
;     ...
;                 for (int m = 0; m < 4; ++m) {
;                     float o[4];
; #pragma unroll
;                     for (int e = 0; e < 4; ++e) {
;                         const float g = acc[ai][0][m][n][e], v = acc[ai][1][m][n][e];
;                         const float gpe = m > 0 ? PG8_ROR1(acc[ai][0][m - 1][n][e]) : hpg[e], vpe = m > 0 ? PG8_ROR1(acc[ai][1][m - 1][n][e]) : hpv[e];
;                         const float gne = m < 3 ? PG8_ROR15(acc[ai][0][m + 1][n][e]) : hng[e], vne = m < 3 ? PG8_ROR15(acc[ai][1][m + 1][n][e]) : hnv[e];
;                         const float gpi = PG8_ROR1(g), vpi = PG8_ROR1(v), gni = PG8_ROR15(g), vni = PG8_ROR15(v);
;                         const float gp = e0 ? gpe : gpi, vp = e0 ? vpe : vpi, gn = e15 ? gne : gni, vn = e15 ? vne : vni;
;                         const float cg = fma_s(w2g[e], gn, fma_s(w1g[e], g, fma_s(w0g[e], gp, bg[e]))), cv = fma_s(w2v[e], vn, fma_s(w1v[e], v, fma_s(w0v[e], vp, bv[e])));
;                         o[e] = (cg * cv) * __builtin_amdgcn_rcpf(1.0f + __builtin_amdgcn_exp2f(cg * -1.4426950408889634f));
;                     }
;                     if (n == 0) { keep[m].x = cvt_pk_bf16(o[0], o[1]); keep[m].y = cvt_pk_bf16(o[2], o[3]); }
;                     else { u32x4 w; w.x = keep[m].x; w.y = keep[m].y; w.z = cvt_pk_bf16(o[0], o[1]); w.w = cvt_pk_bf16(o[2], o[3]);
;                         *(PG8_GAS u32x4*)(act + (size_t)(row0 + ai * HALF + m * 16) * dff + j - 4) = w; }
.LBB0_808:
	s_and_b64 vcc, exec, s[16:17]
	v_mov_b32_e32 v51, 0
	v_mov_b64_e32 v[52:53], 0
	v_mov_b64_e32 v[70:71], 0
	v_mov_b64_e32 v[72:73], 0
	s_cbranch_vccnz .LBB0_810
	ds_read_b128 v[70:73], v134 offset:2064
	ds_read_b128 v[50:53], v134 offset:2576
.LBB0_810:
	v_mov_b32_e32 v115, v114
	v_mov_b32_e32 v117, v116
	v_mov_b32_e32 v84, v114
	v_mov_b32_e32 v85, v114
	v_pk_mul_f32 v[82:83], v[16:17], v[84:85]
	v_pk_mul_f32 v[86:87], v[14:15], v[114:115]
	v_pk_mul_f32 v[8:9], v[8:9], v[84:85]
	v_pk_mul_f32 v[84:85], v[6:7], v[114:115]
	v_mov_b32_e32 v6, v116
	v_mov_b32_e32 v7, v116
	v_pk_mul_f32 v[14:15], v[2:3], v[116:117]
	v_mul_f32_e32 v2, 0xbfb8aa3b, v88
	v_pk_mul_f32 v[16:17], v[10:11], v[116:117]
	v_pk_mul_f32 v[10:11], v[4:5], v[6:7]
	v_exp_f32_e32 v4, v2
	v_mul_f32_e32 v2, 0xbfb8aa3b, v89
	v_pk_mul_f32 v[12:13], v[12:13], v[6:7]
	v_exp_f32_e32 v5, v2
	v_mul_f32_e32 v6, 0xbfb8aa3b, v94
	v_mul_f32_e32 v7, 0xbfb8aa3b, v95
	v_exp_f32_e32 v6, v6
	v_exp_f32_e32 v7, v7
	v_add_f32_e32 v4, 1.0, v4
	v_add_f32_e32 v5, 1.0, v5
	v_rcp_f32_e32 v4, v4
	v_rcp_f32_e32 v5, v5
	v_add_f32_e32 v6, 1.0, v6
	v_add_f32_e32 v7, 1.0, v7
	v_rcp_f32_e32 v6, v6
	v_rcp_f32_e32 v7, v7
	v_pk_mul_f32 v[2:3], v[88:89], v[92:93]
	v_mul_f32_e32 v88, 0xbfb8aa3b, v126
	v_pk_mul_f32 v[2:3], v[2:3], v[4:5]
	v_pk_mul_f32 v[4:5], v[94:95], v[90:91]
	v_cvt_pk_bf16_f32 v3, v2, v3
	v_pk_mul_f32 v[4:5], v[4:5], v[6:7]
	v_mul_f32_e32 v89, 0xbfb8aa3b, v127
	v_cvt_pk_bf16_f32 v2, v4, v5
	v_mul_f32_e32 v4, 0xbfb8aa3b, v130
	v_exp_f32_e32 v6, v4
	v_mul_f32_e32 v4, 0xbfb8aa3b, v131
	v_exp_f32_e32 v7, v4
	v_exp_f32_e32 v88, v88
	v_exp_f32_e32 v89, v89
	v_add_f32_e32 v6, 1.0, v6
	v_add_f32_e32 v7, 1.0, v7
	v_rcp_f32_e32 v6, v6
	v_rcp_f32_e32 v7, v7
	v_add_f32_e32 v88, 1.0, v88
	v_add_f32_e32 v89, 1.0, v89
	v_rcp_f32_e32 v88, v88
	v_rcp_f32_e32 v89, v89
	v_pk_mul_f32 v[4:5], v[130:131], v[132:133]
	v_mul_f32_e32 v90, 0xbfb8aa3b, v118
	v_pk_mul_f32 v[4:5], v[4:5], v[6:7]
	v_pk_mul_f32 v[6:7], v[126:127], v[128:129]
	v_cvt_pk_bf16_f32 v5, v4, v5
	v_pk_mul_f32 v[6:7], v[6:7], v[88:89]
	v_mul_f32_e32 v91, 0xbfb8aa3b, v119
	v_cvt_pk_bf16_f32 v4, v6, v7
	v_mul_f32_e32 v6, 0xbfb8aa3b, v122
	v_exp_f32_e32 v88, v6
	v_mul_f32_e32 v6, 0xbfb8aa3b, v123
	v_exp_f32_e32 v89, v6
	v_exp_f32_e32 v90, v90
	v_exp_f32_e32 v91, v91
	v_add_f32_e32 v88, 1.0, v88
	v_add_f32_e32 v89, 1.0, v89
	v_rcp_f32_e32 v88, v88
	v_rcp_f32_e32 v89, v89
	v_add_f32_e32 v90, 1.0, v90
	v_add_f32_e32 v91, 1.0, v91
	v_rcp_f32_e32 v90, v90
	v_rcp_f32_e32 v91, v91
	v_pk_mul_f32 v[6:7], v[122:123], v[124:125]
	v_mul_f32_e32 v92, 0xbfb8aa3b, v106
	v_pk_mul_f32 v[6:7], v[6:7], v[88:89]
	v_pk_mul_f32 v[88:89], v[118:119], v[120:121]
	v_cvt_pk_bf16_f32 v7, v6, v7
	v_pk_mul_f32 v[88:89], v[88:89], v[90:91]
	v_mul_f32_e32 v93, 0xbfb8aa3b, v107
	v_cvt_pk_bf16_f32 v6, v88, v89
	v_mul_f32_e32 v88, 0xbfb8aa3b, v108
	v_exp_f32_e32 v90, v88
	v_mul_f32_e32 v88, 0xbfb8aa3b, v109
	v_exp_f32_e32 v91, v88
	v_exp_f32_e32 v92, v92
	v_exp_f32_e32 v93, v93
	v_add_f32_e32 v90, 1.0, v90
	v_add_f32_e32 v91, 1.0, v91
	v_rcp_f32_e32 v90, v90
	v_rcp_f32_e32 v91, v91
	v_add_f32_e32 v92, 1.0, v92
	v_add_f32_e32 v93, 1.0, v93
	v_rcp_f32_e32 v92, v92
	v_rcp_f32_e32 v93, v93
	v_pk_mul_f32 v[88:89], v[108:109], v[112:113]
	v_pk_mul_f32 v[88:89], v[88:89], v[90:91]
	v_pk_mul_f32 v[90:91], v[106:107], v[110:111]
	v_cvt_pk_bf16_f32 v89, v88, v89
	v_pk_mul_f32 v[90:91], v[90:91], v[92:93]
	v_cvt_pk_bf16_f32 v88, v90, v91
	s_waitcnt lgkmcnt(1)
	s_waitcnt lgkmcnt(0)
	s_waitcnt lgkmcnt(0)
	v_fma_f32 v179, v58, v38, v66
	s_waitcnt lgkmcnt(0)
	v_fma_f32 v255, v26, v46, v42
	v_fmac_f32_dpp v179, v38, v62 row_shr:1 row_mask:0xf bank_mask:0xf
	v_fma_f32 v181, v59, v39, v67
	v_fma_f32 v185, v27, v47, v43
	v_fmac_f32_dpp v179, v78, v62 row_shl:15 row_mask:0xf bank_mask:0xf
	v_fmac_f32_dpp v255, v46, v34 row_shr:1 row_mask:0xf bank_mask:0xf
	v_fmac_f32_dpp v181, v39, v63 row_shr:1 row_mask:0xf bank_mask:0xf
	v_fmac_f32_dpp v179, v38, v54 row_shl:1 row_mask:0xf bank_mask:0xf
	v_fmac_f32_dpp v255, v74, v34 row_shl:15 row_mask:0xf bank_mask:0xf
	v_fmac_f32_dpp v181, v79, v63 row_shl:15 row_mask:0xf bank_mask:0xf
	v_fmac_f32_dpp v179, v86, v54 row_shr:15 row_mask:0xf bank_mask:0xf
	v_mov_b32_e32 v74, v179
	v_mul_f32_e32 v78, 0xbfb8aa3b, v74
	v_exp_f32_e32 v94, v78
	v_fmac_f32_dpp v255, v46, v30 row_shl:1 row_mask:0xf bank_mask:0xf
	v_add_f32_e32 v90, 1.0, v94
	v_rcp_f32_e32 v90, v90
	v_fmac_f32_dpp v255, v84, v30 row_shr:15 row_mask:0xf bank_mask:0xf
	v_mov_b32_e32 v78, v255
	v_fmac_f32_dpp v181, v39, v55 row_shl:1 row_mask:0xf bank_mask:0xf
	v_fmac_f32_dpp v185, v47, v35 row_shr:1 row_mask:0xf bank_mask:0xf
	v_fma_f32 v183, v60, v40, v68
	v_fma_f32 v179, v28, v48, v44
	v_fmac_f32_dpp v181, v87, v55 row_shr:15 row_mask:0xf bank_mask:0xf
	v_fmac_f32_dpp v185, v75, v35 row_shl:15 row_mask:0xf bank_mask:0xf
	v_mov_b32_e32 v75, v181
	v_mul_f32_e32 v79, 0xbfb8aa3b, v75
	v_exp_f32_e32 v79, v79
	v_fmac_f32_dpp v185, v47, v31 row_shl:1 row_mask:0xf bank_mask:0xf
	v_add_f32_e32 v79, 1.0, v79
	v_rcp_f32_e32 v91, v79
	v_fmac_f32_dpp v185, v85, v31 row_shr:15 row_mask:0xf bank_mask:0xf
	v_mov_b32_e32 v79, v185
	v_pk_mul_f32 v[74:75], v[74:75], v[78:79]
	v_pk_mul_f32 v[74:75], v[74:75], v[90:91]
	v_fmac_f32_dpp v183, v40, v64 row_shr:1 row_mask:0xf bank_mask:0xf
	v_fmac_f32_dpp v179, v48, v36 row_shr:1 row_mask:0xf bank_mask:0xf
	v_fma_f32 v255, v61, v41, v69
	v_fma_f32 v181, v29, v49, v45
	v_fmac_f32_dpp v183, v80, v64 row_shl:15 row_mask:0xf bank_mask:0xf
	v_fmac_f32_dpp v179, v76, v36 row_shl:15 row_mask:0xf bank_mask:0xf
	v_fmac_f32_dpp v255, v41, v65 row_shr:1 row_mask:0xf bank_mask:0xf
; #define PG8_GAS __attribute__((address_space(1)))
; __device__ __forceinline__ unsigned cvt_pk_bf16(float lo, float hi) { const f32x2c v = {lo, hi}; return __builtin_bit_cast(unsigned, __builtin_convertvector(v, bf16x2c)); }
; __device__ __forceinline__ float fma_s(float a, float b, float c) { float d; asm("v_fma_f32 %0, %1, %2, %3" : "=v"(d) : "v"(a), "v"(b), "v"(c)); return d; }
; #define PG8_ROR1(x) dpp_ror1(x)
; #define PG8_ROR15(x) dpp_ror15(x)
;     __device__ __forceinline__ void run(f32x4 (&acc)[2][2][4][2], const Unit& un, int wr, int wc, int fr, int fq, PG8_LAS unsigned char* xl) const {
;     ...
;                 for (int m = 0; m < 4; ++m) {
;                     float o[4];
; #pragma unroll
;                     for (int e = 0; e < 4; ++e) {
;                         const float g = acc[ai][0][m][n][e], v = acc[ai][1][m][n][e];
;                         const float gpe = m > 0 ? PG8_ROR1(acc[ai][0][m - 1][n][e]) : hpg[e], vpe = m > 0 ? PG8_ROR1(acc[ai][1][m - 1][n][e]) : hpv[e];
;                         const float gne = m < 3 ? PG8_ROR15(acc[ai][0][m + 1][n][e]) : hng[e], vne = m < 3 ? PG8_ROR15(acc[ai][1][m + 1][n][e]) : hnv[e];
;                         const float gpi = PG8_ROR1(g), vpi = PG8_ROR1(v), gni = PG8_ROR15(g), vni = PG8_ROR15(v);
;                         const float gp = e0 ? gpe : gpi, vp = e0 ? vpe : vpi, gn = e15 ? gne : gni, vn = e15 ? vne : vni;
;                         const float cg = fma_s(w2g[e], gn, fma_s(w1g[e], g, fma_s(w0g[e], gp, bg[e]))), cv = fma_s(w2v[e], vn, fma_s(w1v[e], v, fma_s(w0v[e], vp, bv[e])));
;                         o[e] = (cg * cv) * __builtin_amdgcn_rcpf(1.0f + __builtin_amdgcn_exp2f(cg * -1.4426950408889634f));
;                     }
;                     if (n == 0) { keep[m].x = cvt_pk_bf16(o[0], o[1]); keep[m].y = cvt_pk_bf16(o[2], o[3]); }
;                     else { u32x4 w; w.x = keep[m].x; w.y = keep[m].y; w.z = cvt_pk_bf16(o[0], o[1]); w.w = cvt_pk_bf16(o[2], o[3]);
;                         *(PG8_GAS u32x4*)(act + (size_t)(row0 + ai * HALF + m * 16) * dff + j - 4) = w; }
	v_fmac_f32_dpp v183, v40, v56 row_shl:1 row_mask:0xf bank_mask:0xf
	v_fmac_f32_dpp v179, v48, v32 row_shl:1 row_mask:0xf bank_mask:0xf
	v_fmac_f32_dpp v255, v81, v65 row_shl:15 row_mask:0xf bank_mask:0xf
	v_fmac_f32_dpp v183, v82, v56 row_shr:15 row_mask:0xf bank_mask:0xf
	v_mov_b32_e32 v76, v183
	v_mul_f32_e32 v78, 0xbfb8aa3b, v76
	v_exp_f32_e32 v90, v78
	v_fmac_f32_dpp v179, v8, v32 row_shr:15 row_mask:0xf bank_mask:0xf
	v_add_f32_e32 v79, 1.0, v90
	v_mov_b32_e32 v78, v179
	v_rcp_f32_e32 v80, v79
	v_fmac_f32_dpp v255, v41, v57 row_shl:1 row_mask:0xf bank_mask:0xf
	v_add_u32_e32 v92, 0x80, v172
	v_fmac_f32_dpp v181, v49, v37 row_shr:1 row_mask:0xf bank_mask:0xf
	v_fmac_f32_dpp v255, v83, v57 row_shr:15 row_mask:0xf bank_mask:0xf
	v_cvt_pk_bf16_f32 v90, v74, v75
	v_fmac_f32_dpp v181, v77, v37 row_shl:15 row_mask:0xf bank_mask:0xf
	v_mov_b32_e32 v77, v255
	v_mul_f32_e32 v79, 0xbfb8aa3b, v77
	v_exp_f32_e32 v79, v79
	v_fmac_f32_dpp v181, v49, v33 row_shl:1 row_mask:0xf bank_mask:0xf
	v_add_f32_e32 v79, 1.0, v79
	v_rcp_f32_e32 v81, v79
	v_fmac_f32_dpp v181, v9, v33 row_shr:15 row_mask:0xf bank_mask:0xf
	v_mov_b32_e32 v79, v181
	v_pk_mul_f32 v[76:77], v[76:77], v[78:79]
	v_pk_mul_f32 v[76:77], v[76:77], v[80:81]
	v_mov_b64_e32 v[74:75], s[24:25]
	v_cvt_pk_bf16_f32 v91, v76, v77
	v_mad_i64_i32 v[76:77], s[14:15], v92, s5, v[74:75]
	v_lshl_add_u64 v[76:77], v[76:77], 0, v[146:147]
	global_store_dwordx4 v[76:77], v[88:91], off
	v_pk_fma_f32 v[250:251], v[26:27], v[84:85], v[42:43]
	v_fma_f32 v185, v58, v86, v66
	v_fma_f32 v183, v59, v87, v67
	v_fmac_f32_dpp v250, v84, v34 row_shr:1 row_mask:0xf bank_mask:0xf
	v_fmac_f32_dpp v251, v85, v35 row_shr:1 row_mask:0xf bank_mask:0xf
	v_fmac_f32_dpp v185, v86, v62 row_shr:1 row_mask:0xf bank_mask:0xf
	v_fmac_f32_dpp v250, v46, v34 row_shl:15 row_mask:0xf bank_mask:0xf
	v_fmac_f32_dpp v251, v47, v35 row_shl:15 row_mask:0xf bank_mask:0xf
	v_fmac_f32_dpp v185, v38, v62 row_shl:15 row_mask:0xf bank_mask:0xf
	v_fmac_f32_dpp v250, v84, v30 row_shl:1 row_mask:0xf bank_mask:0xf
	v_fmac_f32_dpp v251, v85, v31 row_shl:1 row_mask:0xf bank_mask:0xf
	v_fmac_f32_dpp v185, v86, v54 row_shl:1 row_mask:0xf bank_mask:0xf
	v_fmac_f32_dpp v250, v14, v30 row_shr:15 row_mask:0xf bank_mask:0xf
	v_fmac_f32_dpp v251, v15, v31 row_shr:15 row_mask:0xf bank_mask:0xf
	v_mov_b64_e32 v[46:47], v[250:251]
	v_fmac_f32_dpp v185, v16, v54 row_shr:15 row_mask:0xf bank_mask:0xf
	v_mov_b32_e32 v38, v185
	v_mul_f32_e32 v76, 0xbfb8aa3b, v38
	v_fmac_f32_dpp v183, v87, v63 row_shr:1 row_mask:0xf bank_mask:0xf
	v_exp_f32_e32 v76, v76
	v_fma_f32 v179, v60, v82, v68
	v_fmac_f32_dpp v183, v39, v63 row_shl:15 row_mask:0xf bank_mask:0xf
	v_add_f32_e32 v76, 1.0, v76
	v_rcp_f32_e32 v76, v76
	v_fmac_f32_dpp v183, v87, v55 row_shl:1 row_mask:0xf bank_mask:0xf
	v_fmac_f32_dpp v179, v82, v64 row_shr:1 row_mask:0xf bank_mask:0xf
	v_pk_fma_f32 v[252:253], v[28:29], v[8:9], v[44:45]
	v_pk_fma_f32 v[248:249], v[28:29], v[10:11], v[44:45]
	v_pk_fma_f32 v[250:251], v[28:29], v[20:21], v[44:45]
	v_fmac_f32_dpp v183, v17, v55 row_shr:15 row_mask:0xf bank_mask:0xf
	v_mov_b32_e32 v39, v183
	v_mul_f32_e32 v77, 0xbfb8aa3b, v39
	v_exp_f32_e32 v77, v77
	v_pk_mul_f32 v[38:39], v[38:39], v[46:47]
	v_add_f32_e32 v77, 1.0, v77
	v_rcp_f32_e32 v77, v77
	v_fmac_f32_dpp v179, v40, v64 row_shl:15 row_mask:0xf bank_mask:0xf
	v_pk_mul_f32 v[38:39], v[38:39], v[76:77]
	v_fmac_f32_dpp v252, v8, v36 row_shr:1 row_mask:0xf bank_mask:0xf
	v_fmac_f32_dpp v179, v82, v56 row_shl:1 row_mask:0xf bank_mask:0xf
	v_fmac_f32_dpp v253, v9, v37 row_shr:1 row_mask:0xf bank_mask:0xf
	v_fmac_f32_dpp v252, v48, v36 row_shl:15 row_mask:0xf bank_mask:0xf
	v_fmac_f32_dpp v179, v12, v56 row_shr:15 row_mask:0xf bank_mask:0xf
	v_mov_b32_e32 v40, v179
	v_mul_f32_e32 v47, 0xbfb8aa3b, v40
	v_exp_f32_e32 v47, v47
	v_fmac_f32_dpp v253, v49, v37 row_shl:15 row_mask:0xf bank_mask:0xf
	v_add_f32_e32 v46, 1.0, v47
	v_fmac_f32_dpp v252, v8, v32 row_shl:1 row_mask:0xf bank_mask:0xf
	v_fmac_f32_dpp v253, v9, v33 row_shl:1 row_mask:0xf bank_mask:0xf
	v_fma_f32 v255, v61, v83, v69
	v_fmac_f32_dpp v252, v10, v32 row_shr:15 row_mask:0xf bank_mask:0xf
	v_fmac_f32_dpp v253, v11, v33 row_shr:15 row_mask:0xf bank_mask:0xf
	v_fmac_f32_dpp v255, v83, v65 row_shr:1 row_mask:0xf bank_mask:0xf
	v_rcp_f32_e32 v46, v46
	v_fmac_f32_dpp v248, v10, v36 row_shr:1 row_mask:0xf bank_mask:0xf
	v_fmac_f32_dpp v255, v41, v65 row_shl:15 row_mask:0xf bank_mask:0xf
	v_fmac_f32_dpp v249, v11, v37 row_shr:1 row_mask:0xf bank_mask:0xf
	v_fmac_f32_dpp v248, v8, v36 row_shl:15 row_mask:0xf bank_mask:0xf
	v_fmac_f32_dpp v255, v83, v57 row_shl:1 row_mask:0xf bank_mask:0xf
	v_fmac_f32_dpp v249, v9, v37 row_shl:15 row_mask:0xf bank_mask:0xf
	v_mov_b64_e32 v[8:9], v[252:253]
	v_fmac_f32_dpp v255, v13, v57 row_shr:15 row_mask:0xf bank_mask:0xf
	v_mov_b32_e32 v41, v255
	v_pk_mul_f32 v[8:9], v[40:41], v[8:9]
	v_fma_f32 v181, v58, v16, v66
	v_pk_fma_f32 v[252:253], v[26:27], v[14:15], v[42:43]
	v_fmac_f32_dpp v248, v10, v32 row_shl:1 row_mask:0xf bank_mask:0xf
	v_fmac_f32_dpp v181, v16, v62 row_shr:1 row_mask:0xf bank_mask:0xf
	v_fmac_f32_dpp v252, v14, v34 row_shr:1 row_mask:0xf bank_mask:0xf
	v_fmac_f32_dpp v253, v15, v35 row_shr:1 row_mask:0xf bank_mask:0xf
	v_fmac_f32_dpp v181, v86, v62 row_shl:15 row_mask:0xf bank_mask:0xf
	v_fmac_f32_dpp v252, v84, v34 row_shl:15 row_mask:0xf bank_mask:0xf
	v_fmac_f32_dpp v253, v85, v35 row_shl:15 row_mask:0xf bank_mask:0xf
	v_fmac_f32_dpp v181, v16, v54 row_shl:1 row_mask:0xf bank_mask:0xf
	v_fmac_f32_dpp v252, v14, v30 row_shl:1 row_mask:0xf bank_mask:0xf
	v_fmac_f32_dpp v253, v15, v31 row_shl:1 row_mask:0xf bank_mask:0xf
; #define PG8_GAS __attribute__((address_space(1)))
; __device__ __forceinline__ unsigned cvt_pk_bf16(float lo, float hi) { const f32x2c v = {lo, hi}; return __builtin_bit_cast(unsigned, __builtin_convertvector(v, bf16x2c)); }
; __device__ __forceinline__ float fma_s(float a, float b, float c) { float d; asm("v_fma_f32 %0, %1, %2, %3" : "=v"(d) : "v"(a), "v"(b), "v"(c)); return d; }
; #define PG8_ROR1(x) dpp_ror1(x)
; #define PG8_ROR15(x) dpp_ror15(x)
;     __device__ __forceinline__ void run(f32x4 (&acc)[2][2][4][2], const Unit& un, int wr, int wc, int fr, int fq, PG8_LAS unsigned char* xl) const {
;     ...
;                 for (int m = 0; m < 4; ++m) {
;                     float o[4];
; #pragma unroll
;                     for (int e = 0; e < 4; ++e) {
;                         const float g = acc[ai][0][m][n][e], v = acc[ai][1][m][n][e];
;                         const float gpe = m > 0 ? PG8_ROR1(acc[ai][0][m - 1][n][e]) : hpg[e], vpe = m > 0 ? PG8_ROR1(acc[ai][1][m - 1][n][e]) : hpv[e];
;                         const float gne = m < 3 ? PG8_ROR15(acc[ai][0][m + 1][n][e]) : hng[e], vne = m < 3 ? PG8_ROR15(acc[ai][1][m + 1][n][e]) : hnv[e];
;                         const float gpi = PG8_ROR1(g), vpi = PG8_ROR1(v), gni = PG8_ROR15(g), vni = PG8_ROR15(v);
;                         const float gp = e0 ? gpe : gpi, vp = e0 ? vpe : vpi, gn = e15 ? gne : gni, vn = e15 ? vne : vni;
;                         const float cg = fma_s(w2g[e], gn, fma_s(w1g[e], g, fma_s(w0g[e], gp, bg[e]))), cv = fma_s(w2v[e], vn, fma_s(w1v[e], v, fma_s(w0v[e], vp, bv[e])));
;                         o[e] = (cg * cv) * __builtin_amdgcn_rcpf(1.0f + __builtin_amdgcn_exp2f(cg * -1.4426950408889634f));
;                     }
;                     if (n == 0) { keep[m].x = cvt_pk_bf16(o[0], o[1]); keep[m].y = cvt_pk_bf16(o[2], o[3]); }
;                     else { u32x4 w; w.x = keep[m].x; w.y = keep[m].y; w.z = cvt_pk_bf16(o[0], o[1]); w.w = cvt_pk_bf16(o[2], o[3]);
;                         *(PG8_GAS u32x4*)(act + (size_t)(row0 + ai * HALF + m * 16) * dff + j - 4) = w; }
;                 }
;                 __builtin_amdgcn_sched_barrier(0);
;             }
;         }
	v_fmac_f32_dpp v181, v22, v54 row_shr:15 row_mask:0xf bank_mask:0xf
	v_fmac_f32_dpp v252, v18, v30 row_shr:15 row_mask:0xf bank_mask:0xf
	v_fmac_f32_dpp v253, v19, v31 row_shr:15 row_mask:0xf bank_mask:0xf
	v_fmac_f32_dpp v249, v11, v33 row_shl:1 row_mask:0xf bank_mask:0xf
	v_fmac_f32_dpp v248, v20, v32 row_shr:15 row_mask:0xf bank_mask:0xf
	v_fmac_f32_dpp v250, v20, v36 row_shr:1 row_mask:0xf bank_mask:0xf
	v_fmac_f32_dpp v249, v21, v33 row_shr:15 row_mask:0xf bank_mask:0xf
	v_fmac_f32_dpp v251, v21, v37 row_shr:1 row_mask:0xf bank_mask:0xf
	v_fmac_f32_dpp v250, v10, v36 row_shl:15 row_mask:0xf bank_mask:0xf
	v_fma_f32 v185, v59, v17, v67
	v_fmac_f32_dpp v251, v11, v37 row_shl:15 row_mask:0xf bank_mask:0xf
	v_mov_b64_e32 v[10:11], v[248:249]
	v_fmac_f32_dpp v185, v17, v63 row_shr:1 row_mask:0xf bank_mask:0xf
	v_fma_f32 v183, v60, v12, v68
	v_fmac_f32_dpp v250, v20, v32 row_shl:1 row_mask:0xf bank_mask:0xf
	v_fmac_f32_dpp v185, v87, v63 row_shl:15 row_mask:0xf bank_mask:0xf
	v_fmac_f32_dpp v183, v12, v64 row_shr:1 row_mask:0xf bank_mask:0xf
	v_fmac_f32_dpp v251, v21, v33 row_shl:1 row_mask:0xf bank_mask:0xf
	v_fmac_f32_dpp v185, v17, v55 row_shl:1 row_mask:0xf bank_mask:0xf
	v_fmac_f32_dpp v183, v82, v64 row_shl:15 row_mask:0xf bank_mask:0xf
	v_fmac_f32_dpp v250, v52, v32 row_shr:15 row_mask:0xf bank_mask:0xf
	v_fmac_f32_dpp v185, v23, v55 row_shr:15 row_mask:0xf bank_mask:0xf
	v_fmac_f32_dpp v183, v12, v56 row_shl:1 row_mask:0xf bank_mask:0xf
	v_fmac_f32_dpp v251, v53, v33 row_shr:15 row_mask:0xf bank_mask:0xf
	v_fma_f32 v179, v61, v13, v69
	v_fmac_f32_dpp v183, v24, v56 row_shr:15 row_mask:0xf bank_mask:0xf
	v_fma_f32 v255, v58, v22, v66
	v_fmac_f32_dpp v179, v13, v65 row_shr:1 row_mask:0xf bank_mask:0xf
	v_pk_fma_f32 v[248:249], v[26:27], v[18:19], v[42:43]
	v_fmac_f32_dpp v255, v22, v62 row_shr:1 row_mask:0xf bank_mask:0xf
	v_fmac_f32_dpp v179, v83, v65 row_shl:15 row_mask:0xf bank_mask:0xf
	v_mul_f32_e32 v83, 0xbfb8aa3b, v41
	v_exp_f32_e32 v83, v83
	v_fmac_f32_dpp v179, v13, v57 row_shl:1 row_mask:0xf bank_mask:0xf
	v_add_f32_e32 v47, 1.0, v83
	v_rcp_f32_e32 v47, v47
	v_fmac_f32_dpp v179, v25, v57 row_shr:15 row_mask:0xf bank_mask:0xf
	v_pk_mul_f32 v[40:41], v[8:9], v[46:47]
	v_cvt_pk_bf16_f32 v8, v38, v39
	v_add_u32_e32 v38, 0x90, v172
	v_mad_i64_i32 v[38:39], s[14:15], v38, s5, v[74:75]
	v_cvt_pk_bf16_f32 v9, v40, v41
	v_lshl_add_u64 v[38:39], v[38:39], 0, v[146:147]
	global_store_dwordx4 v[38:39], v[6:9], off
	v_fmac_f32_dpp v255, v16, v62 row_shl:15 row_mask:0xf bank_mask:0xf
	v_fmac_f32_dpp v248, v18, v34 row_shr:1 row_mask:0xf bank_mask:0xf
	v_mov_b32_e32 v6, v181
	v_mul_f32_e32 v8, 0xbfb8aa3b, v6
	v_exp_f32_e32 v16, v8
	v_mov_b64_e32 v[8:9], v[252:253]
	v_add_f32_e32 v7, 1.0, v16
	v_rcp_f32_e32 v16, v7
	v_mov_b32_e32 v7, v185
	v_fmac_f32_dpp v255, v22, v54 row_shl:1 row_mask:0xf bank_mask:0xf
	v_fmac_f32_dpp v249, v19, v35 row_shr:1 row_mask:0xf bank_mask:0xf
	v_fmac_f32_dpp v248, v14, v34 row_shl:15 row_mask:0xf bank_mask:0xf
	v_fmac_f32_dpp v255, v70, v54 row_shr:15 row_mask:0xf bank_mask:0xf
	v_fmac_f32_dpp v249, v15, v35 row_shl:15 row_mask:0xf bank_mask:0xf
	v_fmac_f32_dpp v248, v18, v30 row_shl:1 row_mask:0xf bank_mask:0xf
	v_fma_f32 v181, v59, v23, v67
	v_fmac_f32_dpp v249, v19, v31 row_shl:1 row_mask:0xf bank_mask:0xf
	v_fmac_f32_dpp v248, v50, v30 row_shr:15 row_mask:0xf bank_mask:0xf
	v_fmac_f32_dpp v181, v23, v63 row_shr:1 row_mask:0xf bank_mask:0xf
	v_fmac_f32_dpp v249, v51, v31 row_shr:15 row_mask:0xf bank_mask:0xf
	v_fma_f32 v185, v60, v24, v68
	v_fmac_f32_dpp v181, v17, v63 row_shl:15 row_mask:0xf bank_mask:0xf
	v_mul_f32_e32 v17, 0xbfb8aa3b, v7
	v_exp_f32_e32 v17, v17
	v_pk_mul_f32 v[6:7], v[6:7], v[8:9]
	v_add_f32_e32 v17, 1.0, v17
	v_rcp_f32_e32 v17, v17
	v_mov_b32_e32 v8, v183
	v_pk_mul_f32 v[6:7], v[6:7], v[16:17]
	v_cvt_pk_bf16_f32 v6, v6, v7
	v_fmac_f32_dpp v181, v23, v55 row_shl:1 row_mask:0xf bank_mask:0xf
	v_fmac_f32_dpp v185, v24, v64 row_shr:1 row_mask:0xf bank_mask:0xf
	v_fma_f32 v183, v61, v25, v69
	v_fmac_f32_dpp v181, v71, v55 row_shr:15 row_mask:0xf bank_mask:0xf
	v_fmac_f32_dpp v185, v12, v64 row_shl:15 row_mask:0xf bank_mask:0xf
	v_mul_f32_e32 v12, 0xbfb8aa3b, v8
	v_exp_f32_e32 v12, v12
	v_fmac_f32_dpp v185, v24, v56 row_shl:1 row_mask:0xf bank_mask:0xf
	v_add_f32_e32 v9, 1.0, v12
	v_rcp_f32_e32 v12, v9
	v_mov_b32_e32 v9, v179
	v_fmac_f32_dpp v185, v72, v56 row_shr:15 row_mask:0xf bank_mask:0xf
	v_fmac_f32_dpp v183, v25, v65 row_shr:1 row_mask:0xf bank_mask:0xf
	s_nop 0
	s_nop 0
	v_fmac_f32_dpp v183, v13, v65 row_shl:15 row_mask:0xf bank_mask:0xf
	v_mul_f32_e32 v13, 0xbfb8aa3b, v9
	v_exp_f32_e32 v13, v13
	v_pk_mul_f32 v[8:9], v[8:9], v[10:11]
	v_add_f32_e32 v13, 1.0, v13
	v_rcp_f32_e32 v13, v13
	v_fmac_f32_dpp v183, v25, v57 row_shl:1 row_mask:0xf bank_mask:0xf
	v_pk_mul_f32 v[8:9], v[8:9], v[12:13]
	v_cvt_pk_bf16_f32 v7, v8, v9
	v_add_u32_e32 v8, 0xa0, v172
	v_mad_i64_i32 v[8:9], s[14:15], v8, s5, v[74:75]
	v_lshl_add_u64 v[8:9], v[8:9], 0, v[146:147]
	global_store_dwordx4 v[8:9], v[4:7], off
	v_fmac_f32_dpp v183, v73, v57 row_shr:15 row_mask:0xf bank_mask:0xf
	s_nop 0
	v_mov_b32_e32 v4, v255
	v_mul_f32_e32 v6, 0xbfb8aa3b, v4
	v_exp_f32_e32 v8, v6
	v_mov_b64_e32 v[6:7], v[248:249]
	v_add_f32_e32 v5, 1.0, v8
	v_rcp_f32_e32 v8, v5
	v_mov_b32_e32 v5, v181
	v_mul_f32_e32 v9, 0xbfb8aa3b, v5
	v_exp_f32_e32 v9, v9
	v_pk_mul_f32 v[4:5], v[4:5], v[6:7]
	v_add_f32_e32 v9, 1.0, v9
	v_rcp_f32_e32 v9, v9
	v_mov_b32_e32 v6, v185
	v_pk_mul_f32 v[4:5], v[4:5], v[8:9]
	v_mul_f32_e32 v8, 0xbfb8aa3b, v6
	v_exp_f32_e32 v10, v8
	v_mov_b64_e32 v[8:9], v[250:251]
	v_add_f32_e32 v7, 1.0, v10
	v_rcp_f32_e32 v10, v7
	v_cvt_pk_bf16_f32 v4, v4, v5
	v_mov_b32_e32 v7, v183
	v_mul_f32_e32 v11, 0xbfb8aa3b, v7
	v_exp_f32_e32 v11, v11
	v_pk_mul_f32 v[6:7], v[6:7], v[8:9]
	v_add_f32_e32 v11, 1.0, v11
	v_rcp_f32_e32 v11, v11
	s_nop 0
	v_pk_mul_f32 v[6:7], v[6:7], v[10:11]
	v_cvt_pk_bf16_f32 v5, v6, v7
	v_add_u32_e32 v6, 0xb0, v172
	v_mad_i64_i32 v[6:7], s[10:11], v6, s5, v[74:75]
	v_lshl_add_u64 v[6:7], v[6:7], 0, v[146:147]
	global_store_dwordx4 v[6:7], v[2:5], off
	v_mov_b32_e32 v179, 0
	v_mov_b32_e32 v181, 0
	v_mov_b32_e32 v183, 0
	v_mov_b32_e32 v185, 0
	s_andn2_b64 vcc, exec, s[8:9]
	s_mov_b64 s[8:9], -1
	s_cbranch_vccnz .LBB0_766
	s_andn2_b64 vcc, exec, s[30:31]
	s_cbranch_vccnz .LBB0_765
	s_barrier
	s_branch .LBB0_765
